# conv tap loop with packed f32 FMAs on accumulator pairs (weights loaded in descending order)
# speedup vs baseline: 1.0006x; 1.0006x over previous
; #define LAS __attribute__((address_space(3)))
; __device__ __forceinline__ const float* gptr(const float* p) { return (const float*)(const __attribute__((address_space(1))) float*)p; }
; __device__ __forceinline__ int launder_v(int x) { asm volatile("" : "+v"(x)); return x; }
; __device__ __forceinline__ void conv_loop(unsigned char* ws_, const float* const* in_, int l_, LAS unsigned char* lds, int tid, int bid, int G) {
;     const MixCtx X = mk_mix(ws_, in_, l_); tid = launder_v(tid);
;     const int lane = tid & 63, w = tid >> 6;
;     LAS float* U = (LAS float*)lds;
;     const int cch = tid & 255, half = tid >> 8;
;     const float* cw = gptr(X.in[3]) + (size_t)X.l * 31 * CW; float wv[31]; int cwo = cch;
; #pragma unroll
;     for (int k = 0; k < 31; ++k) { wv[k] = cw[cwo]; cwo += CW; asm volatile("" : "+v"(cwo)); }
;     const float bias = gptr(X.in[4])[X.l * CW + cch];
;     const f32x4 gg = *(const f32x4*)(gptr(X.in[5]) + X.l * CW + 4 * lane), bb = *(const f32x4*)(gptr(X.in[6]) + X.l * CW + 4 * lane);
;     for (int cc = bid; cc < BATCH * 8; cc += G) {
;         const int b = cc >> 3, tb = (cc & 7) * 4;
.LBB0_290:
	v_readlane_b32 s8, v253, 10
	s_mov_b64 s[42:43], 0
	s_mov_b32 s2, s48
	v_readlane_b32 s14, v253, 16
	v_readlane_b32 s15, v253, 17
	s_waitcnt lgkmcnt(0)
	s_barrier
	s_mul_i32 s4, s2, 0x7c00
	s_mov_b64 s[46:47], s[14:15]
	s_mul_hi_i32 s3, s2, 0x7c00
	s_waitcnt vmcnt(3)
	v_and_b32_e32 v10, 0xff, v150
	s_add_u32 s26, s46, s4
	s_addc_u32 s27, s47, s3
	v_lshlrev_b32_e32 v1, 2, v10
	v_or_b32_e32 v2, 0x100, v10
	global_load_dword v1, v1, s[26:27]
	v_readlane_b32 s4, v254, 43
	v_ashrrev_i32_e32 v3, 31, v2
	s_waitcnt vmcnt(3)
	v_lshl_add_u64 v[4:5], v[2:3], 2, s[26:27]
	v_add_u32_e32 v2, 0x100, v2
	global_load_dword v101, v[4:5], off
	v_readlane_b32 s5, v254, 44
	v_ashrrev_i32_e32 v3, 31, v2
	v_lshl_add_u64 v[4:5], v[2:3], 2, s[26:27]
	v_add_u32_e32 v2, 0x100, v2
	global_load_dword v100, v[4:5], off
	s_andn2_b64 vcc, exec, s[4:5]
	v_ashrrev_i32_e32 v3, 31, v2
	v_lshl_add_u64 v[4:5], v[2:3], 2, s[26:27]
	v_add_u32_e32 v2, 0x100, v2
	global_load_dword v99, v[4:5], off
	v_readlane_b32 s9, v253, 11
	v_ashrrev_i32_e32 v3, 31, v2
	v_lshl_add_u64 v[4:5], v[2:3], 2, s[26:27]
	v_add_u32_e32 v2, 0x100, v2
	global_load_dword v98, v[4:5], off
	v_readlane_b32 s10, v253, 12
	v_ashrrev_i32_e32 v3, 31, v2
	v_lshl_add_u64 v[4:5], v[2:3], 2, s[26:27]
	v_add_u32_e32 v2, 0x100, v2
	global_load_dword v97, v[4:5], off
	v_readlane_b32 s11, v253, 13
	v_ashrrev_i32_e32 v3, 31, v2
	v_lshl_add_u64 v[4:5], v[2:3], 2, s[26:27]
	v_add_u32_e32 v2, 0x100, v2
	global_load_dword v96, v[4:5], off
	v_readlane_b32 s12, v253, 14
	v_ashrrev_i32_e32 v3, 31, v2
	v_lshl_add_u64 v[4:5], v[2:3], 2, s[26:27]
	v_add_u32_e32 v2, 0x100, v2
	global_load_dword v95, v[4:5], off
	v_readlane_b32 s13, v253, 15
	v_ashrrev_i32_e32 v3, 31, v2
	v_lshl_add_u64 v[4:5], v[2:3], 2, s[26:27]
	v_add_u32_e32 v2, 0x100, v2
	global_load_dword v94, v[4:5], off
	v_readlane_b32 s16, v253, 18
	v_ashrrev_i32_e32 v3, 31, v2
	v_lshl_add_u64 v[4:5], v[2:3], 2, s[26:27]
	v_add_u32_e32 v2, 0x100, v2
	global_load_dword v93, v[4:5], off
	v_readlane_b32 s17, v253, 19
	v_ashrrev_i32_e32 v3, 31, v2
	v_lshl_add_u64 v[4:5], v[2:3], 2, s[26:27]
	v_add_u32_e32 v2, 0x100, v2
	global_load_dword v92, v[4:5], off
	v_readlane_b32 s18, v253, 20
	v_ashrrev_i32_e32 v3, 31, v2
	v_lshl_add_u64 v[4:5], v[2:3], 2, s[26:27]
	v_add_u32_e32 v2, 0x100, v2
	global_load_dword v91, v[4:5], off
	v_readlane_b32 s19, v253, 21
	v_ashrrev_i32_e32 v3, 31, v2
	v_lshl_add_u64 v[4:5], v[2:3], 2, s[26:27]
	v_add_u32_e32 v2, 0x100, v2
	global_load_dword v90, v[4:5], off
	v_readlane_b32 s20, v253, 22
	v_ashrrev_i32_e32 v3, 31, v2
	v_lshl_add_u64 v[4:5], v[2:3], 2, s[26:27]
	v_add_u32_e32 v2, 0x100, v2
	global_load_dword v89, v[4:5], off
	v_readlane_b32 s21, v253, 23
	v_ashrrev_i32_e32 v3, 31, v2
	v_lshl_add_u64 v[4:5], v[2:3], 2, s[26:27]
	v_add_u32_e32 v2, 0x100, v2
	global_load_dword v88, v[4:5], off
	v_readlane_b32 s22, v253, 24
	v_ashrrev_i32_e32 v3, 31, v2
	v_lshl_add_u64 v[4:5], v[2:3], 2, s[26:27]
	v_add_u32_e32 v2, 0x100, v2
	global_load_dword v87, v[4:5], off
	v_readlane_b32 s23, v253, 25
	v_ashrrev_i32_e32 v3, 31, v2
	v_lshl_add_u64 v[4:5], v[2:3], 2, s[26:27]
	v_add_u32_e32 v2, 0x100, v2
	global_load_dword v86, v[4:5], off
	s_nop 0
	v_ashrrev_i32_e32 v3, 31, v2
	v_lshl_add_u64 v[4:5], v[2:3], 2, s[26:27]
	v_add_u32_e32 v2, 0x100, v2
	global_load_dword v85, v[4:5], off
	s_nop 0
	v_ashrrev_i32_e32 v3, 31, v2
	v_lshl_add_u64 v[4:5], v[2:3], 2, s[26:27]
	v_add_u32_e32 v2, 0x100, v2
	global_load_dword v84, v[4:5], off
	s_nop 0
	v_ashrrev_i32_e32 v3, 31, v2
	v_lshl_add_u64 v[4:5], v[2:3], 2, s[26:27]
	v_add_u32_e32 v2, 0x100, v2
	global_load_dword v83, v[4:5], off
	s_nop 0
	v_ashrrev_i32_e32 v3, 31, v2
	v_lshl_add_u64 v[4:5], v[2:3], 2, s[26:27]
	v_add_u32_e32 v2, 0x100, v2
	global_load_dword v82, v[4:5], off
	s_nop 0
	v_ashrrev_i32_e32 v3, 31, v2
	v_lshl_add_u64 v[4:5], v[2:3], 2, s[26:27]
	v_add_u32_e32 v2, 0x100, v2
	global_load_dword v81, v[4:5], off
	s_nop 0
	v_ashrrev_i32_e32 v3, 31, v2
	v_lshl_add_u64 v[4:5], v[2:3], 2, s[26:27]
	v_add_u32_e32 v2, 0x100, v2
	global_load_dword v80, v[4:5], off
	s_nop 0
	v_ashrrev_i32_e32 v3, 31, v2
	v_lshl_add_u64 v[4:5], v[2:3], 2, s[26:27]
	v_add_u32_e32 v2, 0x100, v2
	global_load_dword v79, v[4:5], off
	s_nop 0
	v_ashrrev_i32_e32 v3, 31, v2
	v_lshl_add_u64 v[4:5], v[2:3], 2, s[26:27]
	v_add_u32_e32 v2, 0x100, v2
	global_load_dword v78, v[4:5], off
	s_nop 0
	v_ashrrev_i32_e32 v3, 31, v2
	v_lshl_add_u64 v[4:5], v[2:3], 2, s[26:27]
	v_add_u32_e32 v2, 0x100, v2
	global_load_dword v77, v[4:5], off
	s_nop 0
	v_ashrrev_i32_e32 v3, 31, v2
	v_lshl_add_u64 v[4:5], v[2:3], 2, s[26:27]
	v_add_u32_e32 v2, 0x100, v2
	global_load_dword v76, v[4:5], off
	s_nop 0
	v_ashrrev_i32_e32 v3, 31, v2
	v_lshl_add_u64 v[4:5], v[2:3], 2, s[26:27]
	v_add_u32_e32 v2, 0x100, v2
	global_load_dword v75, v[4:5], off
	s_nop 0
	v_ashrrev_i32_e32 v3, 31, v2
	v_lshl_add_u64 v[4:5], v[2:3], 2, s[26:27]
	v_add_u32_e32 v2, 0x100, v2
	global_load_dword v74, v[4:5], off
	s_nop 0
	v_ashrrev_i32_e32 v3, 31, v2
	v_lshl_add_u64 v[4:5], v[2:3], 2, s[26:27]
	v_add_u32_e32 v2, 0x100, v2
	global_load_dword v73, v[4:5], off
	s_nop 0
	v_ashrrev_i32_e32 v3, 31, v2
	v_lshl_add_u64 v[4:5], v[2:3], 2, s[26:27]
	global_load_dword v72, v[4:5], off
	v_add_u32_e32 v2, 0x100, v2
	s_cbranch_vccnz .LBB0_305
; #define LAS __attribute__((address_space(3)))
; __device__ __forceinline__ const float* gptr(const float* p) { return (const float*)(const __attribute__((address_space(1))) float*)p; }
; __device__ __forceinline__ void conv_loop(unsigned char* ws_, const float* const* in_, int l_, LAS unsigned char* lds, int tid, int bid, int G) {
;     ...
;     const int cch = tid & 255, half = tid >> 8;
;     const float* cw = gptr(X.in[3]) + (size_t)X.l * 31 * CW; float wv[31]; int cwo = cch;
; #pragma unroll
;     for (int k = 0; k < 31; ++k) { wv[k] = cw[cwo]; cwo += CW; asm volatile("" : "+v"(cwo)); }
;     const float bias = gptr(X.in[4])[X.l * CW + cch];
;     const f32x4 gg = *(const f32x4*)(gptr(X.in[5]) + X.l * CW + 4 * lane), bb = *(const f32x4*)(gptr(X.in[6]) + X.l * CW + 4 * lane);
;     for (int cc = bid; cc < BATCH * 8; cc += G) {
;         const int b = cc >> 3, tb = (cc & 7) * 4;
;         const bf16_t* zb = X.Z + (size_t)b * SEQ * INC;
;         u32x4 pa[4], pg[4];
; #pragma unroll
;         for (int i = 0; i < 4; ++i) { const int idx = tid + 512 * i; const int row = idx >> 5, ch = idx & 31; const size_t t = (size_t)(tb * 64 + row);
;             pa[i] = *(const u32x4*)(zb + t * INC + CA0 + ch * 8); pg[i] = *(const u32x4*)(zb + t * INC + CG0 + ch * 8); }
;         __syncthreads();
; #pragma unroll
;         for (int i = 0; i < 2; ++i) { const int idx = tid + 512 * i; if (idx < 30 * 32) { const int row = idx >> 5, ch = idx & 31; const int t = tb * 64 - 30 + row;
;             f32x4 u0 = (f32x4){0.f, 0.f, 0.f, 0.f}, u1 = u0;
;             if (t >= 0) { const u32x4 av = *(const u32x4*)(zb + (size_t)t * INC + CA0 + ch * 8), gv = *(const u32x4*)(zb + (size_t)t * INC + CG0 + ch * 8); conv_glu8(av, gv, u0, u1); }
;             *(LAS f32x4*)(U + row * 256 + ch * 8) = u0; *(LAS f32x4*)(U + row * 256 + ch * 8 + 4) = u1; } }
	v_readlane_b32 s3, v255, 58
	s_add_u32 s3, s3, s42
	v_readlane_b32 s4, v255, 59
	s_addc_u32 s4, s4, s43
	s_add_u32 s7, s3, 0xb500000
	s_addc_u32 s8, s4, 0
	s_lshl_b32 s2, s2, 8
	v_or_b32_e32 v2, s2, v10
	v_readlane_b32 s44, v253, 10
	s_ashr_i32 s3, s2, 31
	v_ashrrev_i32_e32 v3, 31, v2
	v_readlane_b32 s52, v253, 18
	v_readlane_b32 s53, v253, 19
	v_readlane_b32 s54, v253, 20
	s_lshl_b64 s[2:3], s[2:3], 2
	v_readlane_b32 s55, v253, 21
	v_lshl_add_u64 v[2:3], v[2:3], 2, s[52:53]
	s_add_u32 s4, s54, s2
	v_readlane_b32 s56, v253, 22
	global_load_dword v51, v[2:3], off
	s_addc_u32 s5, s55, s3
	v_lshlrev_b32_e32 v2, 4, v150
	v_readlane_b32 s57, v253, 23
	v_and_b32_e32 v11, 0x3f0, v2
	s_add_u32 s2, s56, s2
	s_addc_u32 s3, s57, s3
	global_load_dwordx4 v[2:5], v11, s[4:5]
	global_load_dwordx4 v[6:9], v11, s[2:3]
	v_lshl_add_u32 v104, v10, 2, 0
	v_and_b32_e32 v10, 64, v177
	v_add_u32_e32 v105, 0, v11
	v_add_u32_e32 v10, 64, v10
	v_xor_b32_e32 v11, 1, v177
	v_cmp_lt_i32_e32 vcc, v11, v10
	s_movk_i32 s2, 0x3c0
	v_ashrrev_i32_e32 v14, 3, v150
	v_cndmask_b32_e32 v11, v177, v11, vcc
	v_lshlrev_b32_e32 v106, 2, v11
	v_xor_b32_e32 v11, 2, v177
	v_cmp_lt_i32_e32 vcc, v11, v10
	v_cmp_gt_i32_e64 s[36:37], s2, v150
	s_movk_i32 s2, 0x1c0
	v_cndmask_b32_e32 v11, v177, v11, vcc
	v_lshlrev_b32_e32 v107, 2, v11
	v_xor_b32_e32 v11, 4, v177
	v_cmp_lt_i32_e32 vcc, v11, v10
	v_and_b32_e32 v52, -8, v14
	v_cmp_gt_i32_e64 s[38:39], s2, v150
	v_cndmask_b32_e32 v11, v177, v11, vcc
	v_lshlrev_b32_e32 v108, 2, v11
	v_xor_b32_e32 v11, 8, v177
	v_cmp_lt_i32_e32 vcc, v11, v10
	v_readlane_b32 s2, v255, 13
	v_ashrrev_i32_e32 v53, 31, v52
	v_cndmask_b32_e32 v11, v177, v11, vcc
	v_lshlrev_b32_e32 v109, 2, v11
	v_xor_b32_e32 v11, 16, v177
	v_cmp_lt_i32_e32 vcc, v11, v10
	v_readlane_b32 s3, v255, 14
	v_and_b32_e32 v103, 0xffffffe0, v14
	v_cndmask_b32_e32 v11, v177, v11, vcc
	v_lshlrev_b32_e32 v110, 2, v11
	v_xor_b32_e32 v11, 32, v177
	v_cmp_lt_i32_e32 vcc, v11, v10
	v_or_b32_e32 v54, 7, v14
	v_lshlrev_b64 v[14:15], 11, v[52:53]
	v_cndmask_b32_e32 v10, v177, v11, vcc
	v_lshlrev_b32_e32 v111, 2, v10
	v_add_u32_e32 v10, 0x200, v150
	v_ashrrev_i32_e32 v113, 5, v10
	v_add_u32_e32 v10, 0x400, v150
	v_ashrrev_i32_e32 v114, 5, v10
	v_add_u32_e32 v10, 0x600, v150
	v_ashrrev_i32_e32 v115, 5, v10
	v_and_b32_e32 v10, 63, v150
	v_lshlrev_b32_e32 v10, 3, v10
	v_mov_b32_e32 v11, v0
	v_lshl_add_u64 v[10:11], s[62:63], 0, v[10:11]
	v_lshl_add_u64 v[56:57], s[2:3], 0, v[10:11]
	v_readlane_b32 s2, v253, 8
	v_lshl_add_u64 v[10:11], v[10:11], 0, v[14:15]
	v_readlane_b32 s3, v253, 9
	v_lshlrev_b32_e32 v12, 3, v150
	v_and_b32_e32 v13, 31, v150
	v_ashrrev_i32_e32 v112, 5, v150
	v_lshl_add_u64 v[58:59], s[2:3], 0, v[10:11]
	s_add_u32 s2, s2, s62
	v_readlane_b32 s50, v253, 16
	v_readlane_b32 s51, v253, 17
	v_and_b32_e32 v12, 0xf8, v12
	v_lshl_add_u32 v16, v13, 5, 0
	v_lshlrev_b32_e32 v17, 10, v112
	v_lshlrev_b32_e32 v18, 10, v113
	v_lshlrev_b32_e32 v10, 4, v13
	v_mov_b32_e32 v11, v0
	s_addc_u32 s3, s3, s63
	s_waitcnt vmcnt(35)
	v_lshlrev_b32_e32 v50, 3, v13
	v_lshl_add_u32 v102, v12, 2, 0
	v_or_b32_e32 v116, 1, v52
	v_or_b32_e32 v117, 2, v52
	v_or_b32_e32 v118, 3, v52
	v_or_b32_e32 v119, 4, v52
	v_or_b32_e32 v120, 5, v52
	v_or_b32_e32 v121, 6, v52
	v_ashrrev_i32_e32 v55, 31, v54
	v_lshl_add_u64 v[60:61], s[2:3], 0, v[10:11]
	v_lshlrev_b32_e32 v62, 1, v12
	v_add_u32_e32 v122, v16, v17
	v_add_u32_e32 v123, v16, v18
	v_readlane_b32 s50, v255, 15
	s_mov_b32 s51, s96
	v_readlane_b32 s9, v255, 16
	v_readlane_b32 s45, v253, 11
	v_readlane_b32 s46, v253, 12
	v_readlane_b32 s47, v253, 13
	v_readlane_b32 s48, v253, 14
	v_readlane_b32 s49, v253, 15
	v_readlane_b32 s58, v253, 24
	v_readlane_b32 s59, v253, 25
	s_branch .LBB0_293

; #define LAS __attribute__((address_space(3)))
;     static __device__ __forceinline__ void run(float (&acc)[32], const float (&wv)[31], const LAS float* U, int rb, int cch) {
;         const float uv = U[ring94(ring94(rb + S)) * 256 + cch];
; #pragma unroll
;         for (int o = 0; o < 32; ++o) { constexpr int dummy = 0; const int kk = S - o + dummy; if (kk >= 0 && kk <= 30) acc[o] += wv[kk] * uv; }
;         ConvStep<S + 1>::run(acc, wv, U, rb, cch);
; __device__ __forceinline__ void conv_loop(unsigned char* ws_, const float* const* in_, int l_, LAS unsigned char* lds, int tid, int bid, int G) {
;     ...
;             float acc[32];
; #pragma unroll
;             for (int o = 0; o < 32; ++o) acc[o] = bias;
;             const int rb = base + 32 * half;
;             ConvStep<0>::run(acc, wv, U, rb, cch);
.LBB0_302:
	v_lshl_add_u32 v231, v103, 10, v104
	v_lshl_add_u64 v[46:47], v[46:47], 0, s[0:1]
	v_lshl_add_u64 v[64:65], v[64:65], 0, s[0:1]
	v_lshl_add_u64 v[66:67], v[66:67], 0, s[0:1]
	v_lshl_add_u64 v[68:69], v[68:69], 0, s[0:1]
	s_mov_b32 s2, 0x1e500000
	v_mul_u32_u24_e32 v229, 0x1e0, v103
	v_add_u32_e32 v229, v229, v104
	v_add_u32_e32 v230, 0x10000, v229
	ds_read_b32 v232, v231 offset:0
	ds_read_b32 v234, v231 offset:1024
	ds_read_b32 v236, v231 offset:2048
	ds_read_b32 v238, v231 offset:3072
	ds_read_b32 v240, v231 offset:4096
	ds_read_b32 v242, v231 offset:5120
	ds_read_b32 v244, v231 offset:6144
	ds_read_b32 v246, v231 offset:7168
	v_mov_b32_e32 v192, v73
	v_mov_b32_e32 v193, v74
	v_mov_b32_e32 v194, v75
	v_mov_b32_e32 v195, v76
	v_mov_b32_e32 v196, v77
	v_mov_b32_e32 v197, v78
	v_mov_b32_e32 v198, v79
	v_mov_b32_e32 v199, v80
	v_mov_b32_e32 v200, v81
	v_mov_b32_e32 v201, v82
	v_mov_b32_e32 v202, v83
	v_mov_b32_e32 v203, v84
	v_mov_b32_e32 v204, v85
	v_mov_b32_e32 v205, v86
	v_mov_b32_e32 v206, v87
	v_mov_b32_e32 v207, v88
	v_mov_b32_e32 v208, v89
	v_mov_b32_e32 v209, v90
	v_mov_b32_e32 v210, v91
	v_mov_b32_e32 v211, v92
	v_mov_b32_e32 v212, v93
	v_mov_b32_e32 v213, v94
	v_mov_b32_e32 v166, v95
	v_mov_b32_e32 v167, v96
	v_mov_b32_e32 v168, v97
	v_mov_b32_e32 v169, v98
	v_mov_b32_e32 v170, v99
	v_mov_b32_e32 v171, v100
	v_mov_b32_e32 v172, v101
	v_mov_b32_e32 v173, v1
	v_mov_b32_e32 v124, v51
	v_mov_b32_e32 v125, v51
	v_mov_b32_e32 v126, v51
	v_mov_b32_e32 v127, v51
	v_mov_b32_e32 v128, v51
	v_mov_b32_e32 v129, v51
	v_mov_b32_e32 v130, v51
	v_mov_b32_e32 v131, v51
	v_mov_b32_e32 v132, v51
	v_mov_b32_e32 v133, v51
	v_mov_b32_e32 v134, v51
	v_mov_b32_e32 v135, v51
	v_mov_b32_e32 v136, v51
	v_mov_b32_e32 v137, v51
	v_mov_b32_e32 v148, v51
	v_mov_b32_e32 v149, v51
	v_mov_b32_e32 v150, v51
	v_mov_b32_e32 v151, v51
	v_mov_b32_e32 v152, v51
	v_mov_b32_e32 v153, v51
	v_mov_b32_e32 v154, v51
	v_mov_b32_e32 v155, v51
	v_mov_b32_e32 v156, v51
	v_mov_b32_e32 v157, v51
	v_mov_b32_e32 v158, v51
	v_mov_b32_e32 v159, v51
	v_mov_b32_e32 v160, v51
	v_mov_b32_e32 v161, v51
	v_mov_b32_e32 v162, v51
	v_mov_b32_e32 v163, v51
	v_mov_b32_e32 v164, v51
	v_mov_b32_e32 v165, v51
	ds_read_b32 v248, v231 offset:8192
	s_waitcnt lgkmcnt(8)
	v_fmac_f32_e32 v124, v1, v232
	ds_read_b32 v232, v231 offset:9216
	s_waitcnt lgkmcnt(8)
	v_pk_fma_f32 v[124:125], v[172:173], v[234:235], v[124:125] op_sel_hi:[1,0,1]
	ds_read_b32 v234, v231 offset:10240
	s_waitcnt lgkmcnt(8)
	v_pk_fma_f32 v[124:125], v[100:101], v[236:237], v[124:125] op_sel_hi:[1,0,1]
	v_fmac_f32_e32 v126, v1, v236
	ds_read_b32 v236, v231 offset:11264
	s_waitcnt lgkmcnt(8)
	v_pk_fma_f32 v[124:125], v[170:171], v[238:239], v[124:125] op_sel_hi:[1,0,1]
	v_pk_fma_f32 v[126:127], v[172:173], v[238:239], v[126:127] op_sel_hi:[1,0,1]
	ds_read_b32 v238, v231 offset:12288
	s_waitcnt lgkmcnt(8)
	v_pk_fma_f32 v[124:125], v[98:99], v[240:241], v[124:125] op_sel_hi:[1,0,1]
	v_pk_fma_f32 v[126:127], v[100:101], v[240:241], v[126:127] op_sel_hi:[1,0,1]
	v_fmac_f32_e32 v128, v1, v240
	ds_read_b32 v240, v231 offset:13312
	s_waitcnt lgkmcnt(8)
	v_pk_fma_f32 v[124:125], v[168:169], v[242:243], v[124:125] op_sel_hi:[1,0,1]
	v_pk_fma_f32 v[126:127], v[170:171], v[242:243], v[126:127] op_sel_hi:[1,0,1]
	v_pk_fma_f32 v[128:129], v[172:173], v[242:243], v[128:129] op_sel_hi:[1,0,1]
	ds_read_b32 v242, v231 offset:14336
	s_waitcnt lgkmcnt(8)
	v_pk_fma_f32 v[124:125], v[96:97], v[244:245], v[124:125] op_sel_hi:[1,0,1]
	v_pk_fma_f32 v[126:127], v[98:99], v[244:245], v[126:127] op_sel_hi:[1,0,1]
	v_pk_fma_f32 v[128:129], v[100:101], v[244:245], v[128:129] op_sel_hi:[1,0,1]
	v_fmac_f32_e32 v130, v1, v244
	ds_read_b32 v244, v231 offset:15360
	s_waitcnt lgkmcnt(8)
	v_pk_fma_f32 v[124:125], v[166:167], v[246:247], v[124:125] op_sel_hi:[1,0,1]
	v_pk_fma_f32 v[126:127], v[168:169], v[246:247], v[126:127] op_sel_hi:[1,0,1]
	v_pk_fma_f32 v[128:129], v[170:171], v[246:247], v[128:129] op_sel_hi:[1,0,1]
	v_pk_fma_f32 v[130:131], v[172:173], v[246:247], v[130:131] op_sel_hi:[1,0,1]
	ds_read_b32 v246, v231 offset:16384
	s_waitcnt lgkmcnt(8)
	v_pk_fma_f32 v[124:125], v[94:95], v[248:249], v[124:125] op_sel_hi:[1,0,1]
	v_pk_fma_f32 v[126:127], v[96:97], v[248:249], v[126:127] op_sel_hi:[1,0,1]
	v_pk_fma_f32 v[128:129], v[98:99], v[248:249], v[128:129] op_sel_hi:[1,0,1]
	v_pk_fma_f32 v[130:131], v[100:101], v[248:249], v[130:131] op_sel_hi:[1,0,1]
	v_fmac_f32_e32 v132, v1, v248
	ds_read_b32 v248, v231 offset:17408
	s_waitcnt lgkmcnt(8)
	v_pk_fma_f32 v[124:125], v[212:213], v[232:233], v[124:125] op_sel_hi:[1,0,1]
	v_pk_fma_f32 v[126:127], v[166:167], v[232:233], v[126:127] op_sel_hi:[1,0,1]
	v_pk_fma_f32 v[128:129], v[168:169], v[232:233], v[128:129] op_sel_hi:[1,0,1]
	v_pk_fma_f32 v[130:131], v[170:171], v[232:233], v[130:131] op_sel_hi:[1,0,1]
	v_pk_fma_f32 v[132:133], v[172:173], v[232:233], v[132:133] op_sel_hi:[1,0,1]
	ds_read_b32 v232, v231 offset:18432
	s_waitcnt lgkmcnt(8)
	v_pk_fma_f32 v[124:125], v[92:93], v[234:235], v[124:125] op_sel_hi:[1,0,1]
	v_pk_fma_f32 v[126:127], v[94:95], v[234:235], v[126:127] op_sel_hi:[1,0,1]
	v_pk_fma_f32 v[128:129], v[96:97], v[234:235], v[128:129] op_sel_hi:[1,0,1]
	v_pk_fma_f32 v[130:131], v[98:99], v[234:235], v[130:131] op_sel_hi:[1,0,1]
	v_pk_fma_f32 v[132:133], v[100:101], v[234:235], v[132:133] op_sel_hi:[1,0,1]
	v_fmac_f32_e32 v134, v1, v234
	ds_read_b32 v234, v231 offset:19456
	s_waitcnt lgkmcnt(8)
; #define LAS __attribute__((address_space(3)))
;     static __device__ __forceinline__ void run(float (&acc)[32], const float (&wv)[31], const LAS float* U, int rb, int cch) {
;         const float uv = U[ring94(ring94(rb + S)) * 256 + cch];
; #pragma unroll
;         for (int o = 0; o < 32; ++o) { constexpr int dummy = 0; const int kk = S - o + dummy; if (kk >= 0 && kk <= 30) acc[o] += wv[kk] * uv; }
;         ConvStep<S + 1>::run(acc, wv, U, rb, cch);
	v_pk_fma_f32 v[124:125], v[210:211], v[236:237], v[124:125] op_sel_hi:[1,0,1]
	v_pk_fma_f32 v[126:127], v[212:213], v[236:237], v[126:127] op_sel_hi:[1,0,1]
	v_pk_fma_f32 v[128:129], v[166:167], v[236:237], v[128:129] op_sel_hi:[1,0,1]
	v_pk_fma_f32 v[130:131], v[168:169], v[236:237], v[130:131] op_sel_hi:[1,0,1]
	v_pk_fma_f32 v[132:133], v[170:171], v[236:237], v[132:133] op_sel_hi:[1,0,1]
	v_pk_fma_f32 v[134:135], v[172:173], v[236:237], v[134:135] op_sel_hi:[1,0,1]
	ds_read_b32 v236, v231 offset:20480
	s_waitcnt lgkmcnt(8)
	v_pk_fma_f32 v[124:125], v[90:91], v[238:239], v[124:125] op_sel_hi:[1,0,1]
	v_pk_fma_f32 v[126:127], v[92:93], v[238:239], v[126:127] op_sel_hi:[1,0,1]
	v_pk_fma_f32 v[128:129], v[94:95], v[238:239], v[128:129] op_sel_hi:[1,0,1]
	v_pk_fma_f32 v[130:131], v[96:97], v[238:239], v[130:131] op_sel_hi:[1,0,1]
	v_pk_fma_f32 v[132:133], v[98:99], v[238:239], v[132:133] op_sel_hi:[1,0,1]
	v_pk_fma_f32 v[134:135], v[100:101], v[238:239], v[134:135] op_sel_hi:[1,0,1]
	v_fmac_f32_e32 v136, v1, v238
	ds_read_b32 v238, v231 offset:21504
	s_waitcnt lgkmcnt(8)
	v_pk_fma_f32 v[124:125], v[208:209], v[240:241], v[124:125] op_sel_hi:[1,0,1]
	v_pk_fma_f32 v[126:127], v[210:211], v[240:241], v[126:127] op_sel_hi:[1,0,1]
	v_pk_fma_f32 v[128:129], v[212:213], v[240:241], v[128:129] op_sel_hi:[1,0,1]
	v_pk_fma_f32 v[130:131], v[166:167], v[240:241], v[130:131] op_sel_hi:[1,0,1]
	v_pk_fma_f32 v[132:133], v[168:169], v[240:241], v[132:133] op_sel_hi:[1,0,1]
	v_pk_fma_f32 v[134:135], v[170:171], v[240:241], v[134:135] op_sel_hi:[1,0,1]
	v_pk_fma_f32 v[136:137], v[172:173], v[240:241], v[136:137] op_sel_hi:[1,0,1]
	ds_read_b32 v240, v231 offset:22528
	s_waitcnt lgkmcnt(8)
	v_pk_fma_f32 v[124:125], v[88:89], v[242:243], v[124:125] op_sel_hi:[1,0,1]
	v_pk_fma_f32 v[126:127], v[90:91], v[242:243], v[126:127] op_sel_hi:[1,0,1]
	v_pk_fma_f32 v[128:129], v[92:93], v[242:243], v[128:129] op_sel_hi:[1,0,1]
	v_pk_fma_f32 v[130:131], v[94:95], v[242:243], v[130:131] op_sel_hi:[1,0,1]
	v_pk_fma_f32 v[132:133], v[96:97], v[242:243], v[132:133] op_sel_hi:[1,0,1]
	v_pk_fma_f32 v[134:135], v[98:99], v[242:243], v[134:135] op_sel_hi:[1,0,1]
	v_pk_fma_f32 v[136:137], v[100:101], v[242:243], v[136:137] op_sel_hi:[1,0,1]
	v_fmac_f32_e32 v148, v1, v242
	ds_read_b32 v242, v231 offset:23552
	s_waitcnt lgkmcnt(8)
	v_pk_fma_f32 v[124:125], v[206:207], v[244:245], v[124:125] op_sel_hi:[1,0,1]
	v_pk_fma_f32 v[126:127], v[208:209], v[244:245], v[126:127] op_sel_hi:[1,0,1]
	v_pk_fma_f32 v[128:129], v[210:211], v[244:245], v[128:129] op_sel_hi:[1,0,1]
	v_pk_fma_f32 v[130:131], v[212:213], v[244:245], v[130:131] op_sel_hi:[1,0,1]
	v_pk_fma_f32 v[132:133], v[166:167], v[244:245], v[132:133] op_sel_hi:[1,0,1]
	v_pk_fma_f32 v[134:135], v[168:169], v[244:245], v[134:135] op_sel_hi:[1,0,1]
	v_pk_fma_f32 v[136:137], v[170:171], v[244:245], v[136:137] op_sel_hi:[1,0,1]
	v_pk_fma_f32 v[148:149], v[172:173], v[244:245], v[148:149] op_sel_hi:[1,0,1]
	ds_read_b32 v244, v231 offset:24576
	s_waitcnt lgkmcnt(8)
	v_pk_fma_f32 v[124:125], v[86:87], v[246:247], v[124:125] op_sel_hi:[1,0,1]
	v_pk_fma_f32 v[126:127], v[88:89], v[246:247], v[126:127] op_sel_hi:[1,0,1]
	v_pk_fma_f32 v[128:129], v[90:91], v[246:247], v[128:129] op_sel_hi:[1,0,1]
	v_pk_fma_f32 v[130:131], v[92:93], v[246:247], v[130:131] op_sel_hi:[1,0,1]
	v_pk_fma_f32 v[132:133], v[94:95], v[246:247], v[132:133] op_sel_hi:[1,0,1]
	v_pk_fma_f32 v[134:135], v[96:97], v[246:247], v[134:135] op_sel_hi:[1,0,1]
	v_pk_fma_f32 v[136:137], v[98:99], v[246:247], v[136:137] op_sel_hi:[1,0,1]
	v_pk_fma_f32 v[148:149], v[100:101], v[246:247], v[148:149] op_sel_hi:[1,0,1]
	v_fmac_f32_e32 v150, v1, v246
	ds_read_b32 v246, v231 offset:25600
	s_waitcnt lgkmcnt(8)
	v_pk_fma_f32 v[124:125], v[204:205], v[248:249], v[124:125] op_sel_hi:[1,0,1]
	v_pk_fma_f32 v[126:127], v[206:207], v[248:249], v[126:127] op_sel_hi:[1,0,1]
	v_pk_fma_f32 v[128:129], v[208:209], v[248:249], v[128:129] op_sel_hi:[1,0,1]
	v_pk_fma_f32 v[130:131], v[210:211], v[248:249], v[130:131] op_sel_hi:[1,0,1]
	v_pk_fma_f32 v[132:133], v[212:213], v[248:249], v[132:133] op_sel_hi:[1,0,1]
	v_pk_fma_f32 v[134:135], v[166:167], v[248:249], v[134:135] op_sel_hi:[1,0,1]
	v_pk_fma_f32 v[136:137], v[168:169], v[248:249], v[136:137] op_sel_hi:[1,0,1]
	v_pk_fma_f32 v[148:149], v[170:171], v[248:249], v[148:149] op_sel_hi:[1,0,1]
	v_pk_fma_f32 v[150:151], v[172:173], v[248:249], v[150:151] op_sel_hi:[1,0,1]
	ds_read_b32 v248, v231 offset:26624
	s_waitcnt lgkmcnt(8)
	v_pk_fma_f32 v[124:125], v[84:85], v[232:233], v[124:125] op_sel_hi:[1,0,1]
	v_pk_fma_f32 v[126:127], v[86:87], v[232:233], v[126:127] op_sel_hi:[1,0,1]
	v_pk_fma_f32 v[128:129], v[88:89], v[232:233], v[128:129] op_sel_hi:[1,0,1]
	v_pk_fma_f32 v[130:131], v[90:91], v[232:233], v[130:131] op_sel_hi:[1,0,1]
	v_pk_fma_f32 v[132:133], v[92:93], v[232:233], v[132:133] op_sel_hi:[1,0,1]
	v_pk_fma_f32 v[134:135], v[94:95], v[232:233], v[134:135] op_sel_hi:[1,0,1]
	v_pk_fma_f32 v[136:137], v[96:97], v[232:233], v[136:137] op_sel_hi:[1,0,1]
	v_pk_fma_f32 v[148:149], v[98:99], v[232:233], v[148:149] op_sel_hi:[1,0,1]
	v_pk_fma_f32 v[150:151], v[100:101], v[232:233], v[150:151] op_sel_hi:[1,0,1]
	v_fmac_f32_e32 v152, v1, v232
	ds_read_b32 v232, v231 offset:27648
	s_waitcnt lgkmcnt(8)
; #define LAS __attribute__((address_space(3)))
;     static __device__ __forceinline__ void run(float (&acc)[32], const float (&wv)[31], const LAS float* U, int rb, int cch) {
;         const float uv = U[ring94(ring94(rb + S)) * 256 + cch];
; #pragma unroll
;         for (int o = 0; o < 32; ++o) { constexpr int dummy = 0; const int kk = S - o + dummy; if (kk >= 0 && kk <= 30) acc[o] += wv[kk] * uv; }
;         ConvStep<S + 1>::run(acc, wv, U, rb, cch);
	v_pk_fma_f32 v[124:125], v[202:203], v[234:235], v[124:125] op_sel_hi:[1,0,1]
	v_pk_fma_f32 v[126:127], v[204:205], v[234:235], v[126:127] op_sel_hi:[1,0,1]
	v_pk_fma_f32 v[128:129], v[206:207], v[234:235], v[128:129] op_sel_hi:[1,0,1]
	v_pk_fma_f32 v[130:131], v[208:209], v[234:235], v[130:131] op_sel_hi:[1,0,1]
	v_pk_fma_f32 v[132:133], v[210:211], v[234:235], v[132:133] op_sel_hi:[1,0,1]
	v_pk_fma_f32 v[134:135], v[212:213], v[234:235], v[134:135] op_sel_hi:[1,0,1]
	v_pk_fma_f32 v[136:137], v[166:167], v[234:235], v[136:137] op_sel_hi:[1,0,1]
	v_pk_fma_f32 v[148:149], v[168:169], v[234:235], v[148:149] op_sel_hi:[1,0,1]
	v_pk_fma_f32 v[150:151], v[170:171], v[234:235], v[150:151] op_sel_hi:[1,0,1]
	v_pk_fma_f32 v[152:153], v[172:173], v[234:235], v[152:153] op_sel_hi:[1,0,1]
	ds_read_b32 v234, v231 offset:28672
	s_waitcnt lgkmcnt(8)
	v_pk_fma_f32 v[124:125], v[82:83], v[236:237], v[124:125] op_sel_hi:[1,0,1]
	v_pk_fma_f32 v[126:127], v[84:85], v[236:237], v[126:127] op_sel_hi:[1,0,1]
	v_pk_fma_f32 v[128:129], v[86:87], v[236:237], v[128:129] op_sel_hi:[1,0,1]
	v_pk_fma_f32 v[130:131], v[88:89], v[236:237], v[130:131] op_sel_hi:[1,0,1]
	v_pk_fma_f32 v[132:133], v[90:91], v[236:237], v[132:133] op_sel_hi:[1,0,1]
	v_pk_fma_f32 v[134:135], v[92:93], v[236:237], v[134:135] op_sel_hi:[1,0,1]
	v_pk_fma_f32 v[136:137], v[94:95], v[236:237], v[136:137] op_sel_hi:[1,0,1]
	v_pk_fma_f32 v[148:149], v[96:97], v[236:237], v[148:149] op_sel_hi:[1,0,1]
	v_pk_fma_f32 v[150:151], v[98:99], v[236:237], v[150:151] op_sel_hi:[1,0,1]
	v_pk_fma_f32 v[152:153], v[100:101], v[236:237], v[152:153] op_sel_hi:[1,0,1]
	v_fmac_f32_e32 v154, v1, v236
	ds_read_b32 v236, v231 offset:29696
	s_waitcnt lgkmcnt(8)
	v_pk_fma_f32 v[124:125], v[200:201], v[238:239], v[124:125] op_sel_hi:[1,0,1]
	v_pk_fma_f32 v[126:127], v[202:203], v[238:239], v[126:127] op_sel_hi:[1,0,1]
	v_pk_fma_f32 v[128:129], v[204:205], v[238:239], v[128:129] op_sel_hi:[1,0,1]
	v_pk_fma_f32 v[130:131], v[206:207], v[238:239], v[130:131] op_sel_hi:[1,0,1]
	v_pk_fma_f32 v[132:133], v[208:209], v[238:239], v[132:133] op_sel_hi:[1,0,1]
	v_pk_fma_f32 v[134:135], v[210:211], v[238:239], v[134:135] op_sel_hi:[1,0,1]
	v_pk_fma_f32 v[136:137], v[212:213], v[238:239], v[136:137] op_sel_hi:[1,0,1]
	v_pk_fma_f32 v[148:149], v[166:167], v[238:239], v[148:149] op_sel_hi:[1,0,1]
	v_pk_fma_f32 v[150:151], v[168:169], v[238:239], v[150:151] op_sel_hi:[1,0,1]
	v_pk_fma_f32 v[152:153], v[170:171], v[238:239], v[152:153] op_sel_hi:[1,0,1]
	v_pk_fma_f32 v[154:155], v[172:173], v[238:239], v[154:155] op_sel_hi:[1,0,1]
	ds_read_b32 v238, v231 offset:30720
	s_waitcnt lgkmcnt(8)
	v_pk_fma_f32 v[124:125], v[80:81], v[240:241], v[124:125] op_sel_hi:[1,0,1]
	v_pk_fma_f32 v[126:127], v[82:83], v[240:241], v[126:127] op_sel_hi:[1,0,1]
	v_pk_fma_f32 v[128:129], v[84:85], v[240:241], v[128:129] op_sel_hi:[1,0,1]
	v_pk_fma_f32 v[130:131], v[86:87], v[240:241], v[130:131] op_sel_hi:[1,0,1]
	v_pk_fma_f32 v[132:133], v[88:89], v[240:241], v[132:133] op_sel_hi:[1,0,1]
	v_pk_fma_f32 v[134:135], v[90:91], v[240:241], v[134:135] op_sel_hi:[1,0,1]
	v_pk_fma_f32 v[136:137], v[92:93], v[240:241], v[136:137] op_sel_hi:[1,0,1]
	v_pk_fma_f32 v[148:149], v[94:95], v[240:241], v[148:149] op_sel_hi:[1,0,1]
	v_pk_fma_f32 v[150:151], v[96:97], v[240:241], v[150:151] op_sel_hi:[1,0,1]
	v_pk_fma_f32 v[152:153], v[98:99], v[240:241], v[152:153] op_sel_hi:[1,0,1]
	v_pk_fma_f32 v[154:155], v[100:101], v[240:241], v[154:155] op_sel_hi:[1,0,1]
	v_fmac_f32_e32 v156, v1, v240
	ds_read_b32 v240, v231 offset:31744
	s_waitcnt lgkmcnt(8)
	v_pk_fma_f32 v[124:125], v[198:199], v[242:243], v[124:125] op_sel_hi:[1,0,1]
	v_pk_fma_f32 v[126:127], v[200:201], v[242:243], v[126:127] op_sel_hi:[1,0,1]
	v_pk_fma_f32 v[128:129], v[202:203], v[242:243], v[128:129] op_sel_hi:[1,0,1]
	v_pk_fma_f32 v[130:131], v[204:205], v[242:243], v[130:131] op_sel_hi:[1,0,1]
	v_pk_fma_f32 v[132:133], v[206:207], v[242:243], v[132:133] op_sel_hi:[1,0,1]
	v_pk_fma_f32 v[134:135], v[208:209], v[242:243], v[134:135] op_sel_hi:[1,0,1]
	v_pk_fma_f32 v[136:137], v[210:211], v[242:243], v[136:137] op_sel_hi:[1,0,1]
	v_pk_fma_f32 v[148:149], v[212:213], v[242:243], v[148:149] op_sel_hi:[1,0,1]
	v_pk_fma_f32 v[150:151], v[166:167], v[242:243], v[150:151] op_sel_hi:[1,0,1]
	v_pk_fma_f32 v[152:153], v[168:169], v[242:243], v[152:153] op_sel_hi:[1,0,1]
	v_pk_fma_f32 v[154:155], v[170:171], v[242:243], v[154:155] op_sel_hi:[1,0,1]
	v_pk_fma_f32 v[156:157], v[172:173], v[242:243], v[156:157] op_sel_hi:[1,0,1]
	ds_read_b32 v242, v231 offset:32768
	s_waitcnt lgkmcnt(8)
	v_pk_fma_f32 v[124:125], v[78:79], v[244:245], v[124:125] op_sel_hi:[1,0,1]
	v_pk_fma_f32 v[126:127], v[80:81], v[244:245], v[126:127] op_sel_hi:[1,0,1]
	v_pk_fma_f32 v[128:129], v[82:83], v[244:245], v[128:129] op_sel_hi:[1,0,1]
	v_pk_fma_f32 v[130:131], v[84:85], v[244:245], v[130:131] op_sel_hi:[1,0,1]
	v_pk_fma_f32 v[132:133], v[86:87], v[244:245], v[132:133] op_sel_hi:[1,0,1]
	v_pk_fma_f32 v[134:135], v[88:89], v[244:245], v[134:135] op_sel_hi:[1,0,1]
	v_pk_fma_f32 v[136:137], v[90:91], v[244:245], v[136:137] op_sel_hi:[1,0,1]
	v_pk_fma_f32 v[148:149], v[92:93], v[244:245], v[148:149] op_sel_hi:[1,0,1]
	v_pk_fma_f32 v[150:151], v[94:95], v[244:245], v[150:151] op_sel_hi:[1,0,1]
	v_pk_fma_f32 v[152:153], v[96:97], v[244:245], v[152:153] op_sel_hi:[1,0,1]
	v_pk_fma_f32 v[154:155], v[98:99], v[244:245], v[154:155] op_sel_hi:[1,0,1]
	v_pk_fma_f32 v[156:157], v[100:101], v[244:245], v[156:157] op_sel_hi:[1,0,1]
	v_fmac_f32_e32 v158, v1, v244
	ds_read_b32 v244, v231 offset:33792
	s_waitcnt lgkmcnt(8)
; #define LAS __attribute__((address_space(3)))
;     static __device__ __forceinline__ void run(float (&acc)[32], const float (&wv)[31], const LAS float* U, int rb, int cch) {
;         const float uv = U[ring94(ring94(rb + S)) * 256 + cch];
; #pragma unroll
;         for (int o = 0; o < 32; ++o) { constexpr int dummy = 0; const int kk = S - o + dummy; if (kk >= 0 && kk <= 30) acc[o] += wv[kk] * uv; }
;         ConvStep<S + 1>::run(acc, wv, U, rb, cch);
	v_pk_fma_f32 v[124:125], v[196:197], v[246:247], v[124:125] op_sel_hi:[1,0,1]
	v_pk_fma_f32 v[126:127], v[198:199], v[246:247], v[126:127] op_sel_hi:[1,0,1]
	v_pk_fma_f32 v[128:129], v[200:201], v[246:247], v[128:129] op_sel_hi:[1,0,1]
	v_pk_fma_f32 v[130:131], v[202:203], v[246:247], v[130:131] op_sel_hi:[1,0,1]
	v_pk_fma_f32 v[132:133], v[204:205], v[246:247], v[132:133] op_sel_hi:[1,0,1]
	v_pk_fma_f32 v[134:135], v[206:207], v[246:247], v[134:135] op_sel_hi:[1,0,1]
	v_pk_fma_f32 v[136:137], v[208:209], v[246:247], v[136:137] op_sel_hi:[1,0,1]
	v_pk_fma_f32 v[148:149], v[210:211], v[246:247], v[148:149] op_sel_hi:[1,0,1]
	v_pk_fma_f32 v[150:151], v[212:213], v[246:247], v[150:151] op_sel_hi:[1,0,1]
	v_pk_fma_f32 v[152:153], v[166:167], v[246:247], v[152:153] op_sel_hi:[1,0,1]
	v_pk_fma_f32 v[154:155], v[168:169], v[246:247], v[154:155] op_sel_hi:[1,0,1]
	v_pk_fma_f32 v[156:157], v[170:171], v[246:247], v[156:157] op_sel_hi:[1,0,1]
	v_pk_fma_f32 v[158:159], v[172:173], v[246:247], v[158:159] op_sel_hi:[1,0,1]
	ds_read_b32 v246, v231 offset:34816
	s_waitcnt lgkmcnt(8)
	v_pk_fma_f32 v[124:125], v[76:77], v[248:249], v[124:125] op_sel_hi:[1,0,1]
	v_pk_fma_f32 v[126:127], v[78:79], v[248:249], v[126:127] op_sel_hi:[1,0,1]
	v_pk_fma_f32 v[128:129], v[80:81], v[248:249], v[128:129] op_sel_hi:[1,0,1]
	v_pk_fma_f32 v[130:131], v[82:83], v[248:249], v[130:131] op_sel_hi:[1,0,1]
	v_pk_fma_f32 v[132:133], v[84:85], v[248:249], v[132:133] op_sel_hi:[1,0,1]
	v_pk_fma_f32 v[134:135], v[86:87], v[248:249], v[134:135] op_sel_hi:[1,0,1]
	v_pk_fma_f32 v[136:137], v[88:89], v[248:249], v[136:137] op_sel_hi:[1,0,1]
	v_pk_fma_f32 v[148:149], v[90:91], v[248:249], v[148:149] op_sel_hi:[1,0,1]
	v_pk_fma_f32 v[150:151], v[92:93], v[248:249], v[150:151] op_sel_hi:[1,0,1]
	v_pk_fma_f32 v[152:153], v[94:95], v[248:249], v[152:153] op_sel_hi:[1,0,1]
	v_pk_fma_f32 v[154:155], v[96:97], v[248:249], v[154:155] op_sel_hi:[1,0,1]
	v_pk_fma_f32 v[156:157], v[98:99], v[248:249], v[156:157] op_sel_hi:[1,0,1]
	v_pk_fma_f32 v[158:159], v[100:101], v[248:249], v[158:159] op_sel_hi:[1,0,1]
	v_fmac_f32_e32 v160, v1, v248
	ds_read_b32 v248, v231 offset:35840
	s_waitcnt lgkmcnt(8)
	v_pk_fma_f32 v[124:125], v[194:195], v[232:233], v[124:125] op_sel_hi:[1,0,1]
	v_pk_fma_f32 v[126:127], v[196:197], v[232:233], v[126:127] op_sel_hi:[1,0,1]
	v_pk_fma_f32 v[128:129], v[198:199], v[232:233], v[128:129] op_sel_hi:[1,0,1]
	v_pk_fma_f32 v[130:131], v[200:201], v[232:233], v[130:131] op_sel_hi:[1,0,1]
	v_pk_fma_f32 v[132:133], v[202:203], v[232:233], v[132:133] op_sel_hi:[1,0,1]
	v_pk_fma_f32 v[134:135], v[204:205], v[232:233], v[134:135] op_sel_hi:[1,0,1]
	v_pk_fma_f32 v[136:137], v[206:207], v[232:233], v[136:137] op_sel_hi:[1,0,1]
	v_pk_fma_f32 v[148:149], v[208:209], v[232:233], v[148:149] op_sel_hi:[1,0,1]
	v_pk_fma_f32 v[150:151], v[210:211], v[232:233], v[150:151] op_sel_hi:[1,0,1]
	v_pk_fma_f32 v[152:153], v[212:213], v[232:233], v[152:153] op_sel_hi:[1,0,1]
	v_pk_fma_f32 v[154:155], v[166:167], v[232:233], v[154:155] op_sel_hi:[1,0,1]
	v_pk_fma_f32 v[156:157], v[168:169], v[232:233], v[156:157] op_sel_hi:[1,0,1]
	v_pk_fma_f32 v[158:159], v[170:171], v[232:233], v[158:159] op_sel_hi:[1,0,1]
	v_pk_fma_f32 v[160:161], v[172:173], v[232:233], v[160:161] op_sel_hi:[1,0,1]
	ds_read_b32 v232, v231 offset:36864
	s_waitcnt lgkmcnt(8)
	v_pk_fma_f32 v[124:125], v[74:75], v[234:235], v[124:125] op_sel_hi:[1,0,1]
	v_pk_fma_f32 v[126:127], v[76:77], v[234:235], v[126:127] op_sel_hi:[1,0,1]
	v_pk_fma_f32 v[128:129], v[78:79], v[234:235], v[128:129] op_sel_hi:[1,0,1]
	v_pk_fma_f32 v[130:131], v[80:81], v[234:235], v[130:131] op_sel_hi:[1,0,1]
	v_pk_fma_f32 v[132:133], v[82:83], v[234:235], v[132:133] op_sel_hi:[1,0,1]
	v_pk_fma_f32 v[134:135], v[84:85], v[234:235], v[134:135] op_sel_hi:[1,0,1]
	v_pk_fma_f32 v[136:137], v[86:87], v[234:235], v[136:137] op_sel_hi:[1,0,1]
	v_pk_fma_f32 v[148:149], v[88:89], v[234:235], v[148:149] op_sel_hi:[1,0,1]
	v_pk_fma_f32 v[150:151], v[90:91], v[234:235], v[150:151] op_sel_hi:[1,0,1]
	v_pk_fma_f32 v[152:153], v[92:93], v[234:235], v[152:153] op_sel_hi:[1,0,1]
	v_pk_fma_f32 v[154:155], v[94:95], v[234:235], v[154:155] op_sel_hi:[1,0,1]
	v_pk_fma_f32 v[156:157], v[96:97], v[234:235], v[156:157] op_sel_hi:[1,0,1]
	v_pk_fma_f32 v[158:159], v[98:99], v[234:235], v[158:159] op_sel_hi:[1,0,1]
	v_pk_fma_f32 v[160:161], v[100:101], v[234:235], v[160:161] op_sel_hi:[1,0,1]
	v_fmac_f32_e32 v162, v1, v234
	ds_read_b32 v234, v231 offset:37888
	s_waitcnt lgkmcnt(8)
	v_pk_fma_f32 v[124:125], v[192:193], v[236:237], v[124:125] op_sel_hi:[1,0,1]
	v_pk_fma_f32 v[126:127], v[194:195], v[236:237], v[126:127] op_sel_hi:[1,0,1]
	v_pk_fma_f32 v[128:129], v[196:197], v[236:237], v[128:129] op_sel_hi:[1,0,1]
	v_pk_fma_f32 v[130:131], v[198:199], v[236:237], v[130:131] op_sel_hi:[1,0,1]
	v_pk_fma_f32 v[132:133], v[200:201], v[236:237], v[132:133] op_sel_hi:[1,0,1]
	v_pk_fma_f32 v[134:135], v[202:203], v[236:237], v[134:135] op_sel_hi:[1,0,1]
	v_pk_fma_f32 v[136:137], v[204:205], v[236:237], v[136:137] op_sel_hi:[1,0,1]
	v_pk_fma_f32 v[148:149], v[206:207], v[236:237], v[148:149] op_sel_hi:[1,0,1]
	v_pk_fma_f32 v[150:151], v[208:209], v[236:237], v[150:151] op_sel_hi:[1,0,1]
	v_pk_fma_f32 v[152:153], v[210:211], v[236:237], v[152:153] op_sel_hi:[1,0,1]
	v_pk_fma_f32 v[154:155], v[212:213], v[236:237], v[154:155] op_sel_hi:[1,0,1]
	v_pk_fma_f32 v[156:157], v[166:167], v[236:237], v[156:157] op_sel_hi:[1,0,1]
	v_pk_fma_f32 v[158:159], v[168:169], v[236:237], v[158:159] op_sel_hi:[1,0,1]
	v_pk_fma_f32 v[160:161], v[170:171], v[236:237], v[160:161] op_sel_hi:[1,0,1]
	v_pk_fma_f32 v[162:163], v[172:173], v[236:237], v[162:163] op_sel_hi:[1,0,1]
	ds_read_b32 v236, v231 offset:38912
	s_waitcnt lgkmcnt(8)
; #define LAS __attribute__((address_space(3)))
;     static __device__ __forceinline__ void run(float (&acc)[32], const float (&wv)[31], const LAS float* U, int rb, int cch) {
;         const float uv = U[ring94(ring94(rb + S)) * 256 + cch];
; #pragma unroll
;         for (int o = 0; o < 32; ++o) { constexpr int dummy = 0; const int kk = S - o + dummy; if (kk >= 0 && kk <= 30) acc[o] += wv[kk] * uv; }
;         ConvStep<S + 1>::run(acc, wv, U, rb, cch);
	v_pk_fma_f32 v[124:125], v[72:73], v[238:239], v[124:125] op_sel_hi:[1,0,1]
	v_pk_fma_f32 v[126:127], v[74:75], v[238:239], v[126:127] op_sel_hi:[1,0,1]
	v_pk_fma_f32 v[128:129], v[76:77], v[238:239], v[128:129] op_sel_hi:[1,0,1]
	v_pk_fma_f32 v[130:131], v[78:79], v[238:239], v[130:131] op_sel_hi:[1,0,1]
	v_pk_fma_f32 v[132:133], v[80:81], v[238:239], v[132:133] op_sel_hi:[1,0,1]
	v_pk_fma_f32 v[134:135], v[82:83], v[238:239], v[134:135] op_sel_hi:[1,0,1]
	v_pk_fma_f32 v[136:137], v[84:85], v[238:239], v[136:137] op_sel_hi:[1,0,1]
	v_pk_fma_f32 v[148:149], v[86:87], v[238:239], v[148:149] op_sel_hi:[1,0,1]
	v_pk_fma_f32 v[150:151], v[88:89], v[238:239], v[150:151] op_sel_hi:[1,0,1]
	v_pk_fma_f32 v[152:153], v[90:91], v[238:239], v[152:153] op_sel_hi:[1,0,1]
	v_pk_fma_f32 v[154:155], v[92:93], v[238:239], v[154:155] op_sel_hi:[1,0,1]
	v_pk_fma_f32 v[156:157], v[94:95], v[238:239], v[156:157] op_sel_hi:[1,0,1]
	v_pk_fma_f32 v[158:159], v[96:97], v[238:239], v[158:159] op_sel_hi:[1,0,1]
	v_pk_fma_f32 v[160:161], v[98:99], v[238:239], v[160:161] op_sel_hi:[1,0,1]
	v_pk_fma_f32 v[162:163], v[100:101], v[238:239], v[162:163] op_sel_hi:[1,0,1]
	v_fmac_f32_e32 v164, v1, v238
	ds_read_b32 v238, v231 offset:39936
	s_waitcnt lgkmcnt(8)
	v_fmac_f32_e32 v125, v72, v240
	v_pk_fma_f32 v[126:127], v[192:193], v[240:241], v[126:127] op_sel_hi:[1,0,1]
	v_pk_fma_f32 v[128:129], v[194:195], v[240:241], v[128:129] op_sel_hi:[1,0,1]
	v_pk_fma_f32 v[130:131], v[196:197], v[240:241], v[130:131] op_sel_hi:[1,0,1]
	v_pk_fma_f32 v[132:133], v[198:199], v[240:241], v[132:133] op_sel_hi:[1,0,1]
	v_pk_fma_f32 v[134:135], v[200:201], v[240:241], v[134:135] op_sel_hi:[1,0,1]
	v_pk_fma_f32 v[136:137], v[202:203], v[240:241], v[136:137] op_sel_hi:[1,0,1]
	v_pk_fma_f32 v[148:149], v[204:205], v[240:241], v[148:149] op_sel_hi:[1,0,1]
	v_pk_fma_f32 v[150:151], v[206:207], v[240:241], v[150:151] op_sel_hi:[1,0,1]
	v_pk_fma_f32 v[152:153], v[208:209], v[240:241], v[152:153] op_sel_hi:[1,0,1]
	v_pk_fma_f32 v[154:155], v[210:211], v[240:241], v[154:155] op_sel_hi:[1,0,1]
	v_pk_fma_f32 v[156:157], v[212:213], v[240:241], v[156:157] op_sel_hi:[1,0,1]
	v_pk_fma_f32 v[158:159], v[166:167], v[240:241], v[158:159] op_sel_hi:[1,0,1]
	v_pk_fma_f32 v[160:161], v[168:169], v[240:241], v[160:161] op_sel_hi:[1,0,1]
	v_pk_fma_f32 v[162:163], v[170:171], v[240:241], v[162:163] op_sel_hi:[1,0,1]
	v_pk_fma_f32 v[164:165], v[172:173], v[240:241], v[164:165] op_sel_hi:[1,0,1]
	ds_read_b32 v240, v231 offset:40960
	s_waitcnt lgkmcnt(8)
	v_pk_fma_f32 v[126:127], v[72:73], v[242:243], v[126:127] op_sel_hi:[1,0,1]
	v_pk_fma_f32 v[128:129], v[74:75], v[242:243], v[128:129] op_sel_hi:[1,0,1]
	v_pk_fma_f32 v[130:131], v[76:77], v[242:243], v[130:131] op_sel_hi:[1,0,1]
	v_pk_fma_f32 v[132:133], v[78:79], v[242:243], v[132:133] op_sel_hi:[1,0,1]
	v_pk_fma_f32 v[134:135], v[80:81], v[242:243], v[134:135] op_sel_hi:[1,0,1]
	v_pk_fma_f32 v[136:137], v[82:83], v[242:243], v[136:137] op_sel_hi:[1,0,1]
	v_pk_fma_f32 v[148:149], v[84:85], v[242:243], v[148:149] op_sel_hi:[1,0,1]
	v_pk_fma_f32 v[150:151], v[86:87], v[242:243], v[150:151] op_sel_hi:[1,0,1]
	v_pk_fma_f32 v[152:153], v[88:89], v[242:243], v[152:153] op_sel_hi:[1,0,1]
	v_pk_fma_f32 v[154:155], v[90:91], v[242:243], v[154:155] op_sel_hi:[1,0,1]
	v_pk_fma_f32 v[156:157], v[92:93], v[242:243], v[156:157] op_sel_hi:[1,0,1]
	v_pk_fma_f32 v[158:159], v[94:95], v[242:243], v[158:159] op_sel_hi:[1,0,1]
	v_pk_fma_f32 v[160:161], v[96:97], v[242:243], v[160:161] op_sel_hi:[1,0,1]
	v_pk_fma_f32 v[162:163], v[98:99], v[242:243], v[162:163] op_sel_hi:[1,0,1]
	v_pk_fma_f32 v[164:165], v[100:101], v[242:243], v[164:165] op_sel_hi:[1,0,1]
	ds_read_b32 v242, v231 offset:41984
	s_waitcnt lgkmcnt(8)
	v_fmac_f32_e32 v127, v72, v244
	v_pk_fma_f32 v[128:129], v[192:193], v[244:245], v[128:129] op_sel_hi:[1,0,1]
	v_pk_fma_f32 v[130:131], v[194:195], v[244:245], v[130:131] op_sel_hi:[1,0,1]
	v_pk_fma_f32 v[132:133], v[196:197], v[244:245], v[132:133] op_sel_hi:[1,0,1]
	v_pk_fma_f32 v[134:135], v[198:199], v[244:245], v[134:135] op_sel_hi:[1,0,1]
	v_pk_fma_f32 v[136:137], v[200:201], v[244:245], v[136:137] op_sel_hi:[1,0,1]
	v_pk_fma_f32 v[148:149], v[202:203], v[244:245], v[148:149] op_sel_hi:[1,0,1]
	v_pk_fma_f32 v[150:151], v[204:205], v[244:245], v[150:151] op_sel_hi:[1,0,1]
	v_pk_fma_f32 v[152:153], v[206:207], v[244:245], v[152:153] op_sel_hi:[1,0,1]
	v_pk_fma_f32 v[154:155], v[208:209], v[244:245], v[154:155] op_sel_hi:[1,0,1]
	v_pk_fma_f32 v[156:157], v[210:211], v[244:245], v[156:157] op_sel_hi:[1,0,1]
	v_pk_fma_f32 v[158:159], v[212:213], v[244:245], v[158:159] op_sel_hi:[1,0,1]
	v_pk_fma_f32 v[160:161], v[166:167], v[244:245], v[160:161] op_sel_hi:[1,0,1]
	v_pk_fma_f32 v[162:163], v[168:169], v[244:245], v[162:163] op_sel_hi:[1,0,1]
	v_pk_fma_f32 v[164:165], v[170:171], v[244:245], v[164:165] op_sel_hi:[1,0,1]
	ds_read_b32 v244, v231 offset:43008
	s_waitcnt lgkmcnt(8)
	v_pk_fma_f32 v[128:129], v[72:73], v[246:247], v[128:129] op_sel_hi:[1,0,1]
	v_pk_fma_f32 v[130:131], v[74:75], v[246:247], v[130:131] op_sel_hi:[1,0,1]
	v_pk_fma_f32 v[132:133], v[76:77], v[246:247], v[132:133] op_sel_hi:[1,0,1]
	v_pk_fma_f32 v[134:135], v[78:79], v[246:247], v[134:135] op_sel_hi:[1,0,1]
	v_pk_fma_f32 v[136:137], v[80:81], v[246:247], v[136:137] op_sel_hi:[1,0,1]
	v_pk_fma_f32 v[148:149], v[82:83], v[246:247], v[148:149] op_sel_hi:[1,0,1]
	v_pk_fma_f32 v[150:151], v[84:85], v[246:247], v[150:151] op_sel_hi:[1,0,1]
	v_pk_fma_f32 v[152:153], v[86:87], v[246:247], v[152:153] op_sel_hi:[1,0,1]
	v_pk_fma_f32 v[154:155], v[88:89], v[246:247], v[154:155] op_sel_hi:[1,0,1]
	v_pk_fma_f32 v[156:157], v[90:91], v[246:247], v[156:157] op_sel_hi:[1,0,1]
	v_pk_fma_f32 v[158:159], v[92:93], v[246:247], v[158:159] op_sel_hi:[1,0,1]
	v_pk_fma_f32 v[160:161], v[94:95], v[246:247], v[160:161] op_sel_hi:[1,0,1]
	v_pk_fma_f32 v[162:163], v[96:97], v[246:247], v[162:163] op_sel_hi:[1,0,1]
	v_pk_fma_f32 v[164:165], v[98:99], v[246:247], v[164:165] op_sel_hi:[1,0,1]
	ds_read_b32 v246, v231 offset:44032
	s_waitcnt lgkmcnt(8)
; #define LAS __attribute__((address_space(3)))
;     static __device__ __forceinline__ void run(float (&acc)[32], const float (&wv)[31], const LAS float* U, int rb, int cch) {
;         const float uv = U[ring94(ring94(rb + S)) * 256 + cch];
; #pragma unroll
;         for (int o = 0; o < 32; ++o) { constexpr int dummy = 0; const int kk = S - o + dummy; if (kk >= 0 && kk <= 30) acc[o] += wv[kk] * uv; }
;         ConvStep<S + 1>::run(acc, wv, U, rb, cch);
	v_fmac_f32_e32 v129, v72, v248
	v_pk_fma_f32 v[130:131], v[192:193], v[248:249], v[130:131] op_sel_hi:[1,0,1]
	v_pk_fma_f32 v[132:133], v[194:195], v[248:249], v[132:133] op_sel_hi:[1,0,1]
	v_pk_fma_f32 v[134:135], v[196:197], v[248:249], v[134:135] op_sel_hi:[1,0,1]
	v_pk_fma_f32 v[136:137], v[198:199], v[248:249], v[136:137] op_sel_hi:[1,0,1]
	v_pk_fma_f32 v[148:149], v[200:201], v[248:249], v[148:149] op_sel_hi:[1,0,1]
	v_pk_fma_f32 v[150:151], v[202:203], v[248:249], v[150:151] op_sel_hi:[1,0,1]
	v_pk_fma_f32 v[152:153], v[204:205], v[248:249], v[152:153] op_sel_hi:[1,0,1]
	v_pk_fma_f32 v[154:155], v[206:207], v[248:249], v[154:155] op_sel_hi:[1,0,1]
	v_pk_fma_f32 v[156:157], v[208:209], v[248:249], v[156:157] op_sel_hi:[1,0,1]
	v_pk_fma_f32 v[158:159], v[210:211], v[248:249], v[158:159] op_sel_hi:[1,0,1]
	v_pk_fma_f32 v[160:161], v[212:213], v[248:249], v[160:161] op_sel_hi:[1,0,1]
	v_pk_fma_f32 v[162:163], v[166:167], v[248:249], v[162:163] op_sel_hi:[1,0,1]
	v_pk_fma_f32 v[164:165], v[168:169], v[248:249], v[164:165] op_sel_hi:[1,0,1]
	ds_read_b32 v248, v231 offset:45056
	s_waitcnt lgkmcnt(8)
	v_pk_fma_f32 v[130:131], v[72:73], v[232:233], v[130:131] op_sel_hi:[1,0,1]
	v_pk_fma_f32 v[132:133], v[74:75], v[232:233], v[132:133] op_sel_hi:[1,0,1]
	v_pk_fma_f32 v[134:135], v[76:77], v[232:233], v[134:135] op_sel_hi:[1,0,1]
	v_pk_fma_f32 v[136:137], v[78:79], v[232:233], v[136:137] op_sel_hi:[1,0,1]
	v_pk_fma_f32 v[148:149], v[80:81], v[232:233], v[148:149] op_sel_hi:[1,0,1]
	v_pk_fma_f32 v[150:151], v[82:83], v[232:233], v[150:151] op_sel_hi:[1,0,1]
	v_pk_fma_f32 v[152:153], v[84:85], v[232:233], v[152:153] op_sel_hi:[1,0,1]
	v_pk_fma_f32 v[154:155], v[86:87], v[232:233], v[154:155] op_sel_hi:[1,0,1]
	v_pk_fma_f32 v[156:157], v[88:89], v[232:233], v[156:157] op_sel_hi:[1,0,1]
	v_pk_fma_f32 v[158:159], v[90:91], v[232:233], v[158:159] op_sel_hi:[1,0,1]
	v_pk_fma_f32 v[160:161], v[92:93], v[232:233], v[160:161] op_sel_hi:[1,0,1]
	v_pk_fma_f32 v[162:163], v[94:95], v[232:233], v[162:163] op_sel_hi:[1,0,1]
	v_pk_fma_f32 v[164:165], v[96:97], v[232:233], v[164:165] op_sel_hi:[1,0,1]
	ds_read_b32 v232, v231 offset:46080
	s_waitcnt lgkmcnt(8)
	v_fmac_f32_e32 v131, v72, v234
	v_pk_fma_f32 v[132:133], v[192:193], v[234:235], v[132:133] op_sel_hi:[1,0,1]
	v_pk_fma_f32 v[134:135], v[194:195], v[234:235], v[134:135] op_sel_hi:[1,0,1]
	v_pk_fma_f32 v[136:137], v[196:197], v[234:235], v[136:137] op_sel_hi:[1,0,1]
	v_pk_fma_f32 v[148:149], v[198:199], v[234:235], v[148:149] op_sel_hi:[1,0,1]
	v_pk_fma_f32 v[150:151], v[200:201], v[234:235], v[150:151] op_sel_hi:[1,0,1]
	v_pk_fma_f32 v[152:153], v[202:203], v[234:235], v[152:153] op_sel_hi:[1,0,1]
	v_pk_fma_f32 v[154:155], v[204:205], v[234:235], v[154:155] op_sel_hi:[1,0,1]
	v_pk_fma_f32 v[156:157], v[206:207], v[234:235], v[156:157] op_sel_hi:[1,0,1]
	v_pk_fma_f32 v[158:159], v[208:209], v[234:235], v[158:159] op_sel_hi:[1,0,1]
	v_pk_fma_f32 v[160:161], v[210:211], v[234:235], v[160:161] op_sel_hi:[1,0,1]
	v_pk_fma_f32 v[162:163], v[212:213], v[234:235], v[162:163] op_sel_hi:[1,0,1]
	v_pk_fma_f32 v[164:165], v[166:167], v[234:235], v[164:165] op_sel_hi:[1,0,1]
	ds_read_b32 v234, v231 offset:47104
	s_waitcnt lgkmcnt(8)
	v_pk_fma_f32 v[132:133], v[72:73], v[236:237], v[132:133] op_sel_hi:[1,0,1]
	v_pk_fma_f32 v[134:135], v[74:75], v[236:237], v[134:135] op_sel_hi:[1,0,1]
	v_pk_fma_f32 v[136:137], v[76:77], v[236:237], v[136:137] op_sel_hi:[1,0,1]
	v_pk_fma_f32 v[148:149], v[78:79], v[236:237], v[148:149] op_sel_hi:[1,0,1]
	v_pk_fma_f32 v[150:151], v[80:81], v[236:237], v[150:151] op_sel_hi:[1,0,1]
	v_pk_fma_f32 v[152:153], v[82:83], v[236:237], v[152:153] op_sel_hi:[1,0,1]
	v_pk_fma_f32 v[154:155], v[84:85], v[236:237], v[154:155] op_sel_hi:[1,0,1]
	v_pk_fma_f32 v[156:157], v[86:87], v[236:237], v[156:157] op_sel_hi:[1,0,1]
	v_pk_fma_f32 v[158:159], v[88:89], v[236:237], v[158:159] op_sel_hi:[1,0,1]
	v_pk_fma_f32 v[160:161], v[90:91], v[236:237], v[160:161] op_sel_hi:[1,0,1]
	v_pk_fma_f32 v[162:163], v[92:93], v[236:237], v[162:163] op_sel_hi:[1,0,1]
	v_pk_fma_f32 v[164:165], v[94:95], v[236:237], v[164:165] op_sel_hi:[1,0,1]
	ds_read_b32 v236, v231 offset:48128
	s_waitcnt lgkmcnt(8)
	v_fmac_f32_e32 v133, v72, v238
	v_pk_fma_f32 v[134:135], v[192:193], v[238:239], v[134:135] op_sel_hi:[1,0,1]
	v_pk_fma_f32 v[136:137], v[194:195], v[238:239], v[136:137] op_sel_hi:[1,0,1]
	v_pk_fma_f32 v[148:149], v[196:197], v[238:239], v[148:149] op_sel_hi:[1,0,1]
	v_pk_fma_f32 v[150:151], v[198:199], v[238:239], v[150:151] op_sel_hi:[1,0,1]
	v_pk_fma_f32 v[152:153], v[200:201], v[238:239], v[152:153] op_sel_hi:[1,0,1]
	v_pk_fma_f32 v[154:155], v[202:203], v[238:239], v[154:155] op_sel_hi:[1,0,1]
	v_pk_fma_f32 v[156:157], v[204:205], v[238:239], v[156:157] op_sel_hi:[1,0,1]
	v_pk_fma_f32 v[158:159], v[206:207], v[238:239], v[158:159] op_sel_hi:[1,0,1]
	v_pk_fma_f32 v[160:161], v[208:209], v[238:239], v[160:161] op_sel_hi:[1,0,1]
	v_pk_fma_f32 v[162:163], v[210:211], v[238:239], v[162:163] op_sel_hi:[1,0,1]
	v_pk_fma_f32 v[164:165], v[212:213], v[238:239], v[164:165] op_sel_hi:[1,0,1]
	ds_read_b32 v238, v231 offset:49152
	s_waitcnt lgkmcnt(8)
	v_pk_fma_f32 v[134:135], v[72:73], v[240:241], v[134:135] op_sel_hi:[1,0,1]
	v_pk_fma_f32 v[136:137], v[74:75], v[240:241], v[136:137] op_sel_hi:[1,0,1]
	v_pk_fma_f32 v[148:149], v[76:77], v[240:241], v[148:149] op_sel_hi:[1,0,1]
	v_pk_fma_f32 v[150:151], v[78:79], v[240:241], v[150:151] op_sel_hi:[1,0,1]
	v_pk_fma_f32 v[152:153], v[80:81], v[240:241], v[152:153] op_sel_hi:[1,0,1]
	v_pk_fma_f32 v[154:155], v[82:83], v[240:241], v[154:155] op_sel_hi:[1,0,1]
	v_pk_fma_f32 v[156:157], v[84:85], v[240:241], v[156:157] op_sel_hi:[1,0,1]
	v_pk_fma_f32 v[158:159], v[86:87], v[240:241], v[158:159] op_sel_hi:[1,0,1]
	v_pk_fma_f32 v[160:161], v[88:89], v[240:241], v[160:161] op_sel_hi:[1,0,1]
	v_pk_fma_f32 v[162:163], v[90:91], v[240:241], v[162:163] op_sel_hi:[1,0,1]
	v_pk_fma_f32 v[164:165], v[92:93], v[240:241], v[164:165] op_sel_hi:[1,0,1]
	ds_read_b32 v240, v231 offset:50176
	s_waitcnt lgkmcnt(8)
; #define LAS __attribute__((address_space(3)))
;     static __device__ __forceinline__ void run(float (&acc)[32], const float (&wv)[31], const LAS float* U, int rb, int cch) {
;         const float uv = U[ring94(ring94(rb + S)) * 256 + cch];
; #pragma unroll
;         for (int o = 0; o < 32; ++o) { constexpr int dummy = 0; const int kk = S - o + dummy; if (kk >= 0 && kk <= 30) acc[o] += wv[kk] * uv; }
;         ConvStep<S + 1>::run(acc, wv, U, rb, cch);
	v_fmac_f32_e32 v135, v72, v242
	v_pk_fma_f32 v[136:137], v[192:193], v[242:243], v[136:137] op_sel_hi:[1,0,1]
	v_pk_fma_f32 v[148:149], v[194:195], v[242:243], v[148:149] op_sel_hi:[1,0,1]
	v_pk_fma_f32 v[150:151], v[196:197], v[242:243], v[150:151] op_sel_hi:[1,0,1]
	v_pk_fma_f32 v[152:153], v[198:199], v[242:243], v[152:153] op_sel_hi:[1,0,1]
	v_pk_fma_f32 v[154:155], v[200:201], v[242:243], v[154:155] op_sel_hi:[1,0,1]
	v_pk_fma_f32 v[156:157], v[202:203], v[242:243], v[156:157] op_sel_hi:[1,0,1]
	v_pk_fma_f32 v[158:159], v[204:205], v[242:243], v[158:159] op_sel_hi:[1,0,1]
	v_pk_fma_f32 v[160:161], v[206:207], v[242:243], v[160:161] op_sel_hi:[1,0,1]
	v_pk_fma_f32 v[162:163], v[208:209], v[242:243], v[162:163] op_sel_hi:[1,0,1]
	v_pk_fma_f32 v[164:165], v[210:211], v[242:243], v[164:165] op_sel_hi:[1,0,1]
	ds_read_b32 v242, v231 offset:51200
	s_waitcnt lgkmcnt(8)
	v_pk_fma_f32 v[136:137], v[72:73], v[244:245], v[136:137] op_sel_hi:[1,0,1]
	v_pk_fma_f32 v[148:149], v[74:75], v[244:245], v[148:149] op_sel_hi:[1,0,1]
	v_pk_fma_f32 v[150:151], v[76:77], v[244:245], v[150:151] op_sel_hi:[1,0,1]
	v_pk_fma_f32 v[152:153], v[78:79], v[244:245], v[152:153] op_sel_hi:[1,0,1]
	v_pk_fma_f32 v[154:155], v[80:81], v[244:245], v[154:155] op_sel_hi:[1,0,1]
	v_pk_fma_f32 v[156:157], v[82:83], v[244:245], v[156:157] op_sel_hi:[1,0,1]
	v_pk_fma_f32 v[158:159], v[84:85], v[244:245], v[158:159] op_sel_hi:[1,0,1]
	v_pk_fma_f32 v[160:161], v[86:87], v[244:245], v[160:161] op_sel_hi:[1,0,1]
	v_pk_fma_f32 v[162:163], v[88:89], v[244:245], v[162:163] op_sel_hi:[1,0,1]
	v_pk_fma_f32 v[164:165], v[90:91], v[244:245], v[164:165] op_sel_hi:[1,0,1]
	ds_read_b32 v244, v231 offset:52224
	s_waitcnt lgkmcnt(8)
	v_fmac_f32_e32 v137, v72, v246
	v_pk_fma_f32 v[148:149], v[192:193], v[246:247], v[148:149] op_sel_hi:[1,0,1]
	v_pk_fma_f32 v[150:151], v[194:195], v[246:247], v[150:151] op_sel_hi:[1,0,1]
	v_pk_fma_f32 v[152:153], v[196:197], v[246:247], v[152:153] op_sel_hi:[1,0,1]
	v_pk_fma_f32 v[154:155], v[198:199], v[246:247], v[154:155] op_sel_hi:[1,0,1]
	v_pk_fma_f32 v[156:157], v[200:201], v[246:247], v[156:157] op_sel_hi:[1,0,1]
	v_pk_fma_f32 v[158:159], v[202:203], v[246:247], v[158:159] op_sel_hi:[1,0,1]
	v_pk_fma_f32 v[160:161], v[204:205], v[246:247], v[160:161] op_sel_hi:[1,0,1]
	v_pk_fma_f32 v[162:163], v[206:207], v[246:247], v[162:163] op_sel_hi:[1,0,1]
	v_pk_fma_f32 v[164:165], v[208:209], v[246:247], v[164:165] op_sel_hi:[1,0,1]
	ds_read_b32 v246, v231 offset:53248
	s_waitcnt lgkmcnt(8)
	v_pk_fma_f32 v[148:149], v[72:73], v[248:249], v[148:149] op_sel_hi:[1,0,1]
	v_pk_fma_f32 v[150:151], v[74:75], v[248:249], v[150:151] op_sel_hi:[1,0,1]
	v_pk_fma_f32 v[152:153], v[76:77], v[248:249], v[152:153] op_sel_hi:[1,0,1]
	v_pk_fma_f32 v[154:155], v[78:79], v[248:249], v[154:155] op_sel_hi:[1,0,1]
	v_pk_fma_f32 v[156:157], v[80:81], v[248:249], v[156:157] op_sel_hi:[1,0,1]
	v_pk_fma_f32 v[158:159], v[82:83], v[248:249], v[158:159] op_sel_hi:[1,0,1]
	v_pk_fma_f32 v[160:161], v[84:85], v[248:249], v[160:161] op_sel_hi:[1,0,1]
	v_pk_fma_f32 v[162:163], v[86:87], v[248:249], v[162:163] op_sel_hi:[1,0,1]
	v_pk_fma_f32 v[164:165], v[88:89], v[248:249], v[164:165] op_sel_hi:[1,0,1]
	ds_read_b32 v248, v231 offset:54272
	s_waitcnt lgkmcnt(8)
	v_fmac_f32_e32 v149, v72, v232
	v_pk_fma_f32 v[150:151], v[192:193], v[232:233], v[150:151] op_sel_hi:[1,0,1]
	v_pk_fma_f32 v[152:153], v[194:195], v[232:233], v[152:153] op_sel_hi:[1,0,1]
	v_pk_fma_f32 v[154:155], v[196:197], v[232:233], v[154:155] op_sel_hi:[1,0,1]
	v_pk_fma_f32 v[156:157], v[198:199], v[232:233], v[156:157] op_sel_hi:[1,0,1]
	v_pk_fma_f32 v[158:159], v[200:201], v[232:233], v[158:159] op_sel_hi:[1,0,1]
	v_pk_fma_f32 v[160:161], v[202:203], v[232:233], v[160:161] op_sel_hi:[1,0,1]
	v_pk_fma_f32 v[162:163], v[204:205], v[232:233], v[162:163] op_sel_hi:[1,0,1]
	v_pk_fma_f32 v[164:165], v[206:207], v[232:233], v[164:165] op_sel_hi:[1,0,1]
	ds_read_b32 v232, v231 offset:55296
	s_waitcnt lgkmcnt(8)
	v_pk_fma_f32 v[150:151], v[72:73], v[234:235], v[150:151] op_sel_hi:[1,0,1]
	v_pk_fma_f32 v[152:153], v[74:75], v[234:235], v[152:153] op_sel_hi:[1,0,1]
	v_pk_fma_f32 v[154:155], v[76:77], v[234:235], v[154:155] op_sel_hi:[1,0,1]
	v_pk_fma_f32 v[156:157], v[78:79], v[234:235], v[156:157] op_sel_hi:[1,0,1]
	v_pk_fma_f32 v[158:159], v[80:81], v[234:235], v[158:159] op_sel_hi:[1,0,1]
	v_pk_fma_f32 v[160:161], v[82:83], v[234:235], v[160:161] op_sel_hi:[1,0,1]
	v_pk_fma_f32 v[162:163], v[84:85], v[234:235], v[162:163] op_sel_hi:[1,0,1]
	v_pk_fma_f32 v[164:165], v[86:87], v[234:235], v[164:165] op_sel_hi:[1,0,1]
	ds_read_b32 v234, v231 offset:56320
	s_waitcnt lgkmcnt(8)
	v_fmac_f32_e32 v151, v72, v236
	v_pk_fma_f32 v[152:153], v[192:193], v[236:237], v[152:153] op_sel_hi:[1,0,1]
	v_pk_fma_f32 v[154:155], v[194:195], v[236:237], v[154:155] op_sel_hi:[1,0,1]
	v_pk_fma_f32 v[156:157], v[196:197], v[236:237], v[156:157] op_sel_hi:[1,0,1]
	v_pk_fma_f32 v[158:159], v[198:199], v[236:237], v[158:159] op_sel_hi:[1,0,1]
	v_pk_fma_f32 v[160:161], v[200:201], v[236:237], v[160:161] op_sel_hi:[1,0,1]
	v_pk_fma_f32 v[162:163], v[202:203], v[236:237], v[162:163] op_sel_hi:[1,0,1]
	v_pk_fma_f32 v[164:165], v[204:205], v[236:237], v[164:165] op_sel_hi:[1,0,1]
	ds_read_b32 v236, v231 offset:57344
	s_waitcnt lgkmcnt(8)
	v_pk_fma_f32 v[152:153], v[72:73], v[238:239], v[152:153] op_sel_hi:[1,0,1]
	v_pk_fma_f32 v[154:155], v[74:75], v[238:239], v[154:155] op_sel_hi:[1,0,1]
	v_pk_fma_f32 v[156:157], v[76:77], v[238:239], v[156:157] op_sel_hi:[1,0,1]
	v_pk_fma_f32 v[158:159], v[78:79], v[238:239], v[158:159] op_sel_hi:[1,0,1]
	v_pk_fma_f32 v[160:161], v[80:81], v[238:239], v[160:161] op_sel_hi:[1,0,1]
	v_pk_fma_f32 v[162:163], v[82:83], v[238:239], v[162:163] op_sel_hi:[1,0,1]
	v_pk_fma_f32 v[164:165], v[84:85], v[238:239], v[164:165] op_sel_hi:[1,0,1]
	ds_read_b32 v238, v231 offset:58368
	s_waitcnt lgkmcnt(8)
; #define LAS __attribute__((address_space(3)))
;     static __device__ __forceinline__ void run(float (&acc)[32], const float (&wv)[31], const LAS float* U, int rb, int cch) {
;         const float uv = U[ring94(ring94(rb + S)) * 256 + cch];
; #pragma unroll
;         for (int o = 0; o < 32; ++o) { constexpr int dummy = 0; const int kk = S - o + dummy; if (kk >= 0 && kk <= 30) acc[o] += wv[kk] * uv; }
;         ConvStep<S + 1>::run(acc, wv, U, rb, cch);
; __device__ __forceinline__ void conv_loop(unsigned char* ws_, const float* const* in_, int l_, LAS unsigned char* lds, int tid, int bid, int G) {
;     ...
;             __syncthreads();
; #pragma unroll
;             for (int o = 0; o < 32; ++o) U[ring94(ring94(rb + o)) * 256 + cch] = acc[o];
	v_fmac_f32_e32 v153, v72, v240
	v_pk_fma_f32 v[154:155], v[192:193], v[240:241], v[154:155] op_sel_hi:[1,0,1]
	v_pk_fma_f32 v[156:157], v[194:195], v[240:241], v[156:157] op_sel_hi:[1,0,1]
	v_pk_fma_f32 v[158:159], v[196:197], v[240:241], v[158:159] op_sel_hi:[1,0,1]
	v_pk_fma_f32 v[160:161], v[198:199], v[240:241], v[160:161] op_sel_hi:[1,0,1]
	v_pk_fma_f32 v[162:163], v[200:201], v[240:241], v[162:163] op_sel_hi:[1,0,1]
	v_pk_fma_f32 v[164:165], v[202:203], v[240:241], v[164:165] op_sel_hi:[1,0,1]
	ds_read_b32 v240, v231 offset:59392
	s_waitcnt lgkmcnt(8)
	v_pk_fma_f32 v[154:155], v[72:73], v[242:243], v[154:155] op_sel_hi:[1,0,1]
	v_pk_fma_f32 v[156:157], v[74:75], v[242:243], v[156:157] op_sel_hi:[1,0,1]
	v_pk_fma_f32 v[158:159], v[76:77], v[242:243], v[158:159] op_sel_hi:[1,0,1]
	v_pk_fma_f32 v[160:161], v[78:79], v[242:243], v[160:161] op_sel_hi:[1,0,1]
	v_pk_fma_f32 v[162:163], v[80:81], v[242:243], v[162:163] op_sel_hi:[1,0,1]
	v_pk_fma_f32 v[164:165], v[82:83], v[242:243], v[164:165] op_sel_hi:[1,0,1]
	ds_read_b32 v242, v231 offset:60416
	s_waitcnt lgkmcnt(8)
	v_fmac_f32_e32 v155, v72, v244
	v_pk_fma_f32 v[156:157], v[192:193], v[244:245], v[156:157] op_sel_hi:[1,0,1]
	v_pk_fma_f32 v[158:159], v[194:195], v[244:245], v[158:159] op_sel_hi:[1,0,1]
	v_pk_fma_f32 v[160:161], v[196:197], v[244:245], v[160:161] op_sel_hi:[1,0,1]
	v_pk_fma_f32 v[162:163], v[198:199], v[244:245], v[162:163] op_sel_hi:[1,0,1]
	v_pk_fma_f32 v[164:165], v[200:201], v[244:245], v[164:165] op_sel_hi:[1,0,1]
	ds_read_b32 v244, v231 offset:61440
	s_waitcnt lgkmcnt(8)
	v_pk_fma_f32 v[156:157], v[72:73], v[246:247], v[156:157] op_sel_hi:[1,0,1]
	v_pk_fma_f32 v[158:159], v[74:75], v[246:247], v[158:159] op_sel_hi:[1,0,1]
	v_pk_fma_f32 v[160:161], v[76:77], v[246:247], v[160:161] op_sel_hi:[1,0,1]
	v_pk_fma_f32 v[162:163], v[78:79], v[246:247], v[162:163] op_sel_hi:[1,0,1]
	v_pk_fma_f32 v[164:165], v[80:81], v[246:247], v[164:165] op_sel_hi:[1,0,1]
	ds_read_b32 v246, v231 offset:62464
	s_waitcnt lgkmcnt(8)
	v_fmac_f32_e32 v157, v72, v248
	v_pk_fma_f32 v[158:159], v[192:193], v[248:249], v[158:159] op_sel_hi:[1,0,1]
	v_pk_fma_f32 v[160:161], v[194:195], v[248:249], v[160:161] op_sel_hi:[1,0,1]
	v_pk_fma_f32 v[162:163], v[196:197], v[248:249], v[162:163] op_sel_hi:[1,0,1]
	v_pk_fma_f32 v[164:165], v[198:199], v[248:249], v[164:165] op_sel_hi:[1,0,1]
	s_waitcnt lgkmcnt(7)
	v_pk_fma_f32 v[158:159], v[72:73], v[232:233], v[158:159] op_sel_hi:[1,0,1]
	v_pk_fma_f32 v[160:161], v[74:75], v[232:233], v[160:161] op_sel_hi:[1,0,1]
	v_pk_fma_f32 v[162:163], v[76:77], v[232:233], v[162:163] op_sel_hi:[1,0,1]
	v_pk_fma_f32 v[164:165], v[78:79], v[232:233], v[164:165] op_sel_hi:[1,0,1]
	s_waitcnt lgkmcnt(6)
	v_fmac_f32_e32 v159, v72, v234
	v_pk_fma_f32 v[160:161], v[192:193], v[234:235], v[160:161] op_sel_hi:[1,0,1]
	v_pk_fma_f32 v[162:163], v[194:195], v[234:235], v[162:163] op_sel_hi:[1,0,1]
	v_pk_fma_f32 v[164:165], v[196:197], v[234:235], v[164:165] op_sel_hi:[1,0,1]
	s_waitcnt lgkmcnt(5)
	v_pk_fma_f32 v[160:161], v[72:73], v[236:237], v[160:161] op_sel_hi:[1,0,1]
	v_pk_fma_f32 v[162:163], v[74:75], v[236:237], v[162:163] op_sel_hi:[1,0,1]
	v_pk_fma_f32 v[164:165], v[76:77], v[236:237], v[164:165] op_sel_hi:[1,0,1]
	s_waitcnt lgkmcnt(4)
	v_fmac_f32_e32 v161, v72, v238
	v_pk_fma_f32 v[162:163], v[192:193], v[238:239], v[162:163] op_sel_hi:[1,0,1]
	v_pk_fma_f32 v[164:165], v[194:195], v[238:239], v[164:165] op_sel_hi:[1,0,1]
	s_waitcnt lgkmcnt(3)
	v_pk_fma_f32 v[162:163], v[72:73], v[240:241], v[162:163] op_sel_hi:[1,0,1]
	v_pk_fma_f32 v[164:165], v[74:75], v[240:241], v[164:165] op_sel_hi:[1,0,1]
	s_waitcnt lgkmcnt(2)
	v_fmac_f32_e32 v163, v72, v242
	v_pk_fma_f32 v[164:165], v[192:193], v[242:243], v[164:165] op_sel_hi:[1,0,1]
	s_waitcnt lgkmcnt(1)
	v_pk_fma_f32 v[164:165], v[72:73], v[244:245], v[164:165] op_sel_hi:[1,0,1]
	s_waitcnt lgkmcnt(0)
	v_fmac_f32_e32 v165, v72, v246
	ds_read_b32 v214, v230 offset:0
	ds_read_b32 v215, v230 offset:1024
	ds_read_b32 v216, v230 offset:2048
	ds_read_b32 v217, v230 offset:3072
	ds_read_b32 v218, v230 offset:4096
	ds_read_b32 v219, v230 offset:5120
	ds_read_b32 v220, v230 offset:6144
	ds_read_b32 v221, v230 offset:7168
	ds_read_b32 v222, v230 offset:8192
	ds_read_b32 v223, v230 offset:9216
	ds_read_b32 v224, v230 offset:10240
	ds_read_b32 v225, v230 offset:11264
	ds_read_b32 v226, v230 offset:12288
	ds_read_b32 v227, v230 offset:13312
	ds_read_b32 v228, v230 offset:14336
	s_barrier
	ds_write_b32 v231, v124 offset:0
	ds_write_b32 v231, v125 offset:1024
	ds_write_b32 v231, v126 offset:2048
	ds_write_b32 v231, v127 offset:3072
	ds_write_b32 v231, v128 offset:4096
	ds_write_b32 v231, v129 offset:5120
	ds_write_b32 v231, v130 offset:6144
	ds_write_b32 v231, v131 offset:7168
	ds_write_b32 v231, v132 offset:8192
	ds_write_b32 v231, v133 offset:9216
	ds_write_b32 v231, v134 offset:10240
	ds_write_b32 v231, v135 offset:11264
	ds_write_b32 v231, v136 offset:12288
	ds_write_b32 v231, v137 offset:13312
	ds_write_b32 v231, v148 offset:14336
	ds_write_b32 v231, v149 offset:15360
	ds_write_b32 v231, v150 offset:16384
	ds_write_b32 v231, v151 offset:17408
	ds_write_b32 v231, v152 offset:18432
	ds_write_b32 v231, v153 offset:19456
	ds_write_b32 v231, v154 offset:20480
	ds_write_b32 v231, v155 offset:21504
	ds_write_b32 v231, v156 offset:22528
	ds_write_b32 v231, v157 offset:23552
	ds_write_b32 v231, v158 offset:24576
	ds_write_b32 v231, v159 offset:25600
	ds_write_b32 v231, v160 offset:26624
	ds_write_b32 v231, v161 offset:27648
	ds_write_b32 v231, v162 offset:28672
	ds_write_b32 v231, v163 offset:29696
	ds_write_b32 v231, v164 offset:30720
	ds_write_b32 v231, v165 offset:31744
	v_add_u32_e32 v63, s26, v52
	v_cmp_lt_i32_e32 vcc, s91, v63
	v_lshlrev_b32_e32 v63, 10, v63
	v_add_u32_e32 v70, 0xfffe8800, v63
	v_cndmask_b32_e32 v63, v63, v70, vcc
	v_add_u32_e32 v63, v105, v63
	s_waitcnt lgkmcnt(0)
	s_barrier
; #define LAS __attribute__((address_space(3)))
; __device__ __forceinline__ float wave_sum(float v) {
; #pragma unroll
;     for (int o = 1; o < 64; o <<= 1) v += __shfl_xor(v, o);
;     return v;
; __device__ __forceinline__ void conv_loop(unsigned char* ws_, const float* const* in_, int l_, LAS unsigned char* lds, int tid, int bid, int G) {
;     ...
;             __syncthreads();
; #pragma unroll
;             for (int i = 0; i < 8; ++i) { const int tok = 8 * w + i; f32x4 v = *(LAS f32x4*)(U + ring94(base + tok) * 256 + 4 * lane);
;                 const float mean = wave_sum((v[0] + v[1]) + (v[2] + v[3])) * (1.0f / 256.0f);
	v_lshl_add_u32 v188, v52, 10, v105
	ds_read_b128 v[124:127], v188 offset:0
	ds_read_b128 v[128:131], v188 offset:1024
	ds_read_b128 v[132:135], v188 offset:2048
	ds_read_b128 v[148:151], v188 offset:3072
	ds_read_b128 v[152:155], v188 offset:4096
	ds_read_b128 v[156:159], v188 offset:5120
	ds_read_b128 v[160:163], v188 offset:6144
	ds_read_b128 v[164:167], v188 offset:7168
	s_mov_b32 s76, 0x1000
	s_mov_b32 s77, 0
	v_lshl_add_u64 v[206:207], v[48:49], 0, s[42:43]
	v_lshl_add_u64 v[48:49], v[48:49], 0, s[74:75]
	v_lshl_add_u64 v[44:45], v[44:45], 0, s[74:75]
	v_lshl_add_u64 v[42:43], v[42:43], 0, s[74:75]
	v_lshl_add_u64 v[208:209], v[206:207], 0, s[76:77]
	v_lshl_add_u64 v[210:211], v[208:209], 0, s[76:77]
	v_lshl_add_u64 v[212:213], v[210:211], 0, s[76:77]
	s_add_i32 s27, s27, -1
	s_waitcnt lgkmcnt(7)
	v_add_f32_e32 v168, v125, v124
	v_add_f32_e32 v194, v126, v127
	s_waitcnt lgkmcnt(6)
	v_add_f32_e32 v169, v129, v128
	v_add_f32_e32 v195, v130, v131
	s_waitcnt lgkmcnt(5)
	v_add_f32_e32 v170, v133, v132
	v_add_f32_e32 v196, v134, v135
	s_waitcnt lgkmcnt(4)
	v_add_f32_e32 v171, v149, v148
	v_add_f32_e32 v197, v150, v151
	s_waitcnt lgkmcnt(3)
	v_add_f32_e32 v172, v153, v152
	v_add_f32_e32 v198, v154, v155
	s_waitcnt lgkmcnt(2)
	v_add_f32_e32 v173, v157, v156
	v_add_f32_e32 v199, v158, v159
	s_waitcnt lgkmcnt(1)
	v_add_f32_e32 v192, v161, v160
	v_add_f32_e32 v200, v162, v163
	s_waitcnt lgkmcnt(0)
	v_add_f32_e32 v193, v165, v164
	v_add_f32_e32 v201, v166, v167
	v_add_f32_e32 v168, v168, v194
	v_add_f32_e32 v169, v169, v195
	v_add_f32_e32 v170, v170, v196
	v_add_f32_e32 v171, v171, v197
	v_add_f32_e32 v172, v172, v198
	v_add_f32_e32 v173, v173, v199
	v_add_f32_e32 v192, v192, v200
	v_add_f32_e32 v193, v193, v201
	v_add_f32_dpp v168, v168, v168 quad_perm:[1,0,3,2] row_mask:0xf bank_mask:0xf
	v_add_f32_dpp v169, v169, v169 quad_perm:[1,0,3,2] row_mask:0xf bank_mask:0xf
	v_add_f32_dpp v170, v170, v170 quad_perm:[1,0,3,2] row_mask:0xf bank_mask:0xf
	v_add_f32_dpp v171, v171, v171 quad_perm:[1,0,3,2] row_mask:0xf bank_mask:0xf
	v_add_f32_dpp v172, v172, v172 quad_perm:[1,0,3,2] row_mask:0xf bank_mask:0xf
	v_add_f32_dpp v173, v173, v173 quad_perm:[1,0,3,2] row_mask:0xf bank_mask:0xf
	v_add_f32_dpp v192, v192, v192 quad_perm:[1,0,3,2] row_mask:0xf bank_mask:0xf
	v_add_f32_dpp v193, v193, v193 quad_perm:[1,0,3,2] row_mask:0xf bank_mask:0xf
	v_add_f32_dpp v168, v168, v168 quad_perm:[2,3,0,1] row_mask:0xf bank_mask:0xf
	v_add_f32_dpp v169, v169, v169 quad_perm:[2,3,0,1] row_mask:0xf bank_mask:0xf
	v_add_f32_dpp v170, v170, v170 quad_perm:[2,3,0,1] row_mask:0xf bank_mask:0xf
	v_add_f32_dpp v171, v171, v171 quad_perm:[2,3,0,1] row_mask:0xf bank_mask:0xf
	v_add_f32_dpp v172, v172, v172 quad_perm:[2,3,0,1] row_mask:0xf bank_mask:0xf
	v_add_f32_dpp v173, v173, v173 quad_perm:[2,3,0,1] row_mask:0xf bank_mask:0xf
	v_add_f32_dpp v192, v192, v192 quad_perm:[2,3,0,1] row_mask:0xf bank_mask:0xf
	v_add_f32_dpp v193, v193, v193 quad_perm:[2,3,0,1] row_mask:0xf bank_mask:0xf
	v_add_f32_dpp v168, v168, v168 row_half_mirror row_mask:0xf bank_mask:0xf
	v_add_f32_dpp v169, v169, v169 row_half_mirror row_mask:0xf bank_mask:0xf
	v_add_f32_dpp v170, v170, v170 row_half_mirror row_mask:0xf bank_mask:0xf
	v_add_f32_dpp v171, v171, v171 row_half_mirror row_mask:0xf bank_mask:0xf
	v_add_f32_dpp v172, v172, v172 row_half_mirror row_mask:0xf bank_mask:0xf
	v_add_f32_dpp v173, v173, v173 row_half_mirror row_mask:0xf bank_mask:0xf
	v_add_f32_dpp v192, v192, v192 row_half_mirror row_mask:0xf bank_mask:0xf
	v_add_f32_dpp v193, v193, v193 row_half_mirror row_mask:0xf bank_mask:0xf
	v_add_f32_dpp v168, v168, v168 row_mirror row_mask:0xf bank_mask:0xf
	v_add_f32_dpp v169, v169, v169 row_mirror row_mask:0xf bank_mask:0xf
	v_add_f32_dpp v170, v170, v170 row_mirror row_mask:0xf bank_mask:0xf
	v_add_f32_dpp v171, v171, v171 row_mirror row_mask:0xf bank_mask:0xf
	v_add_f32_dpp v172, v172, v172 row_mirror row_mask:0xf bank_mask:0xf
	v_add_f32_dpp v173, v173, v173 row_mirror row_mask:0xf bank_mask:0xf
	v_add_f32_dpp v192, v192, v192 row_mirror row_mask:0xf bank_mask:0xf
	v_add_f32_dpp v193, v193, v193 row_mirror row_mask:0xf bank_mask:0xf
	ds_bpermute_b32 v194, v110, v168
	ds_bpermute_b32 v195, v110, v169
	ds_bpermute_b32 v196, v110, v170
	ds_bpermute_b32 v197, v110, v171
	ds_bpermute_b32 v198, v110, v172
	ds_bpermute_b32 v199, v110, v173
	ds_bpermute_b32 v200, v110, v192
	ds_bpermute_b32 v201, v110, v193
	s_waitcnt lgkmcnt(7)
	v_add_f32_e32 v168, v168, v194
	s_waitcnt lgkmcnt(6)
	v_add_f32_e32 v169, v169, v195
	s_waitcnt lgkmcnt(5)
	v_add_f32_e32 v170, v170, v196
	s_waitcnt lgkmcnt(4)
	v_add_f32_e32 v171, v171, v197
	s_waitcnt lgkmcnt(3)
	v_add_f32_e32 v172, v172, v198
	s_waitcnt lgkmcnt(2)
	v_add_f32_e32 v173, v173, v199
	s_waitcnt lgkmcnt(1)
	v_add_f32_e32 v192, v192, v200
	s_waitcnt lgkmcnt(0)
	v_add_f32_e32 v193, v193, v201
	ds_bpermute_b32 v194, v111, v168
	ds_bpermute_b32 v195, v111, v169
	ds_bpermute_b32 v196, v111, v170
	ds_bpermute_b32 v197, v111, v171
	ds_bpermute_b32 v198, v111, v172
	ds_bpermute_b32 v199, v111, v173
	ds_bpermute_b32 v200, v111, v192
	ds_bpermute_b32 v201, v111, v193
	s_waitcnt lgkmcnt(7)
	v_add_f32_e32 v168, v168, v194
	s_waitcnt lgkmcnt(6)
	v_add_f32_e32 v169, v169, v195
	s_waitcnt lgkmcnt(5)
	v_add_f32_e32 v170, v170, v196
	s_waitcnt lgkmcnt(4)
	v_add_f32_e32 v171, v171, v197
	s_waitcnt lgkmcnt(3)
	v_add_f32_e32 v172, v172, v198
	s_waitcnt lgkmcnt(2)
	v_add_f32_e32 v173, v173, v199
	s_waitcnt lgkmcnt(1)
	v_add_f32_e32 v192, v192, v200
	s_waitcnt lgkmcnt(0)
; __device__ __forceinline__ void conv_loop(unsigned char* ws_, const float* const* in_, int l_, LAS unsigned char* lds, int tid, int bid, int G) {
;     ...
;                 const float mean = wave_sum((v[0] + v[1]) + (v[2] + v[3])) * (1.0f / 256.0f);
;                 v = v - mean; const float var = wave_sum((v[0] * v[0] + v[1] * v[1]) + (v[2] * v[2] + v[3] * v[3])) * (1.0f / 256.0f);
	v_add_f32_e32 v193, v193, v201
	v_fmamk_f32 v124, v168, 0xbb800000, v124
	v_fmamk_f32 v125, v168, 0xbb800000, v125
	v_fmamk_f32 v126, v168, 0xbb800000, v126
	v_fmamk_f32 v127, v168, 0xbb800000, v127
	v_fmamk_f32 v128, v169, 0xbb800000, v128
	v_fmamk_f32 v129, v169, 0xbb800000, v129
	v_fmamk_f32 v130, v169, 0xbb800000, v130
	v_fmamk_f32 v131, v169, 0xbb800000, v131
	v_fmamk_f32 v132, v170, 0xbb800000, v132
	v_fmamk_f32 v133, v170, 0xbb800000, v133
	v_fmamk_f32 v134, v170, 0xbb800000, v134
	v_fmamk_f32 v135, v170, 0xbb800000, v135
	v_fmamk_f32 v148, v171, 0xbb800000, v148
	v_fmamk_f32 v149, v171, 0xbb800000, v149
	v_fmamk_f32 v150, v171, 0xbb800000, v150
	v_fmamk_f32 v151, v171, 0xbb800000, v151
	v_fmamk_f32 v152, v172, 0xbb800000, v152
	v_fmamk_f32 v153, v172, 0xbb800000, v153
	v_fmamk_f32 v154, v172, 0xbb800000, v154
	v_fmamk_f32 v155, v172, 0xbb800000, v155
	v_fmamk_f32 v156, v173, 0xbb800000, v156
	v_fmamk_f32 v157, v173, 0xbb800000, v157
	v_fmamk_f32 v158, v173, 0xbb800000, v158
	v_fmamk_f32 v159, v173, 0xbb800000, v159
	v_fmamk_f32 v160, v192, 0xbb800000, v160
	v_fmamk_f32 v161, v192, 0xbb800000, v161
	v_fmamk_f32 v162, v192, 0xbb800000, v162
	v_fmamk_f32 v163, v192, 0xbb800000, v163
	v_fmamk_f32 v164, v193, 0xbb800000, v164
	v_fmamk_f32 v165, v193, 0xbb800000, v165
	v_fmamk_f32 v166, v193, 0xbb800000, v166
	v_fmamk_f32 v167, v193, 0xbb800000, v167
	v_mul_f32_e32 v168, v125, v125
	v_mul_f32_e32 v194, v124, v124
	v_mul_f32_e32 v169, v129, v129
	v_mul_f32_e32 v195, v128, v128
	v_mul_f32_e32 v170, v133, v133
	v_mul_f32_e32 v196, v132, v132
	v_mul_f32_e32 v171, v149, v149
	v_mul_f32_e32 v197, v148, v148
	v_mul_f32_e32 v172, v153, v153
	v_mul_f32_e32 v198, v152, v152
	v_mul_f32_e32 v173, v157, v157
	v_mul_f32_e32 v199, v156, v156
	v_mul_f32_e32 v192, v161, v161
	v_mul_f32_e32 v200, v160, v160
	v_mul_f32_e32 v193, v165, v165
	v_mul_f32_e32 v201, v164, v164
	v_add_f32_e32 v168, v168, v194
	v_add_f32_e32 v169, v169, v195
	v_add_f32_e32 v170, v170, v196
	v_add_f32_e32 v171, v171, v197
	v_add_f32_e32 v172, v172, v198
	v_add_f32_e32 v173, v173, v199
	v_add_f32_e32 v192, v192, v200
	v_add_f32_e32 v193, v193, v201
	v_mul_f32_e32 v194, v126, v126
	v_mul_f32_e32 v195, v130, v130
	v_mul_f32_e32 v196, v134, v134
	v_mul_f32_e32 v197, v150, v150
	v_mul_f32_e32 v198, v154, v154
	v_mul_f32_e32 v199, v158, v158
	v_mul_f32_e32 v200, v162, v162
	v_mul_f32_e32 v201, v166, v166
	v_mul_f32_e32 v202, v127, v127
	v_mul_f32_e32 v203, v131, v131
	v_mul_f32_e32 v204, v135, v135
	v_mul_f32_e32 v205, v151, v151
	v_add_f32_e32 v194, v194, v202
	v_add_f32_e32 v195, v195, v203
	v_add_f32_e32 v196, v196, v204
	v_add_f32_e32 v197, v197, v205
	v_mul_f32_e32 v202, v155, v155
	v_mul_f32_e32 v203, v159, v159
	v_mul_f32_e32 v204, v163, v163
	v_mul_f32_e32 v205, v167, v167
	v_add_f32_e32 v198, v198, v202
	v_add_f32_e32 v199, v199, v203
	v_add_f32_e32 v200, v200, v204
	v_add_f32_e32 v201, v201, v205
	v_add_f32_e32 v168, v168, v194
	v_add_f32_e32 v169, v169, v195
	v_add_f32_e32 v170, v170, v196
	v_add_f32_e32 v171, v171, v197
	v_add_f32_e32 v172, v172, v198
	v_add_f32_e32 v173, v173, v199
	v_add_f32_e32 v192, v192, v200
	v_add_f32_e32 v193, v193, v201
	v_add_f32_dpp v168, v168, v168 quad_perm:[1,0,3,2] row_mask:0xf bank_mask:0xf
	v_add_f32_dpp v169, v169, v169 quad_perm:[1,0,3,2] row_mask:0xf bank_mask:0xf
	v_add_f32_dpp v170, v170, v170 quad_perm:[1,0,3,2] row_mask:0xf bank_mask:0xf
	v_add_f32_dpp v171, v171, v171 quad_perm:[1,0,3,2] row_mask:0xf bank_mask:0xf
	v_add_f32_dpp v172, v172, v172 quad_perm:[1,0,3,2] row_mask:0xf bank_mask:0xf
	v_add_f32_dpp v173, v173, v173 quad_perm:[1,0,3,2] row_mask:0xf bank_mask:0xf
	v_add_f32_dpp v192, v192, v192 quad_perm:[1,0,3,2] row_mask:0xf bank_mask:0xf
	v_add_f32_dpp v193, v193, v193 quad_perm:[1,0,3,2] row_mask:0xf bank_mask:0xf
	v_add_f32_dpp v168, v168, v168 quad_perm:[2,3,0,1] row_mask:0xf bank_mask:0xf
	v_add_f32_dpp v169, v169, v169 quad_perm:[2,3,0,1] row_mask:0xf bank_mask:0xf
	v_add_f32_dpp v170, v170, v170 quad_perm:[2,3,0,1] row_mask:0xf bank_mask:0xf
	v_add_f32_dpp v171, v171, v171 quad_perm:[2,3,0,1] row_mask:0xf bank_mask:0xf
	v_add_f32_dpp v172, v172, v172 quad_perm:[2,3,0,1] row_mask:0xf bank_mask:0xf
	v_add_f32_dpp v173, v173, v173 quad_perm:[2,3,0,1] row_mask:0xf bank_mask:0xf
	v_add_f32_dpp v192, v192, v192 quad_perm:[2,3,0,1] row_mask:0xf bank_mask:0xf
	v_add_f32_dpp v193, v193, v193 quad_perm:[2,3,0,1] row_mask:0xf bank_mask:0xf
	v_add_f32_dpp v168, v168, v168 row_half_mirror row_mask:0xf bank_mask:0xf
	v_add_f32_dpp v169, v169, v169 row_half_mirror row_mask:0xf bank_mask:0xf
	v_add_f32_dpp v170, v170, v170 row_half_mirror row_mask:0xf bank_mask:0xf
	v_add_f32_dpp v171, v171, v171 row_half_mirror row_mask:0xf bank_mask:0xf
	v_add_f32_dpp v172, v172, v172 row_half_mirror row_mask:0xf bank_mask:0xf
	v_add_f32_dpp v173, v173, v173 row_half_mirror row_mask:0xf bank_mask:0xf
	v_add_f32_dpp v192, v192, v192 row_half_mirror row_mask:0xf bank_mask:0xf
	v_add_f32_dpp v193, v193, v193 row_half_mirror row_mask:0xf bank_mask:0xf
	v_add_f32_dpp v168, v168, v168 row_mirror row_mask:0xf bank_mask:0xf
	v_add_f32_dpp v169, v169, v169 row_mirror row_mask:0xf bank_mask:0xf
	v_add_f32_dpp v170, v170, v170 row_mirror row_mask:0xf bank_mask:0xf
	v_add_f32_dpp v171, v171, v171 row_mirror row_mask:0xf bank_mask:0xf
	v_add_f32_dpp v172, v172, v172 row_mirror row_mask:0xf bank_mask:0xf
	v_add_f32_dpp v173, v173, v173 row_mirror row_mask:0xf bank_mask:0xf
	v_add_f32_dpp v192, v192, v192 row_mirror row_mask:0xf bank_mask:0xf
	v_add_f32_dpp v193, v193, v193 row_mirror row_mask:0xf bank_mask:0xf
	ds_bpermute_b32 v194, v110, v168
	ds_bpermute_b32 v195, v110, v169
	ds_bpermute_b32 v196, v110, v170
	ds_bpermute_b32 v197, v110, v171
	ds_bpermute_b32 v198, v110, v172
	ds_bpermute_b32 v199, v110, v173
	ds_bpermute_b32 v200, v110, v192
	ds_bpermute_b32 v201, v110, v193
	s_waitcnt lgkmcnt(7)
; __device__ __forceinline__ float sigmoidf_(float x) { return __builtin_amdgcn_rcpf(1.f + __expf(-x)); }
; __device__ __forceinline__ void conv_loop(unsigned char* ws_, const float* const* in_, int l_, LAS unsigned char* lds, int tid, int bid, int G) {
;     ...
;                 v = v - mean; const float var = wave_sum((v[0] * v[0] + v[1] * v[1]) + (v[2] * v[2] + v[3] * v[3])) * (1.0f / 256.0f);
;                 const float rstd = rsqrtf(var + LN_EPS); f32x4 y = v * rstd * gg + bb;
; #pragma unroll
;                 for (int e = 0; e < 4; ++e) y[e] = y[e] * sigmoidf_(y[e]);
	v_add_f32_e32 v168, v168, v194
	s_waitcnt lgkmcnt(6)
	v_add_f32_e32 v169, v169, v195
	s_waitcnt lgkmcnt(5)
	v_add_f32_e32 v170, v170, v196
	s_waitcnt lgkmcnt(4)
	v_add_f32_e32 v171, v171, v197
	s_waitcnt lgkmcnt(3)
	v_add_f32_e32 v172, v172, v198
	s_waitcnt lgkmcnt(2)
	v_add_f32_e32 v173, v173, v199
	s_waitcnt lgkmcnt(1)
	v_add_f32_e32 v192, v192, v200
	s_waitcnt lgkmcnt(0)
	v_add_f32_e32 v193, v193, v201
	ds_bpermute_b32 v194, v111, v168
	ds_bpermute_b32 v195, v111, v169
	ds_bpermute_b32 v196, v111, v170
	ds_bpermute_b32 v197, v111, v171
	ds_bpermute_b32 v198, v111, v172
	ds_bpermute_b32 v199, v111, v173
	ds_bpermute_b32 v200, v111, v192
	ds_bpermute_b32 v201, v111, v193
	s_waitcnt lgkmcnt(7)
	v_add_f32_e32 v168, v168, v194
	s_waitcnt lgkmcnt(6)
	v_add_f32_e32 v169, v169, v195
	s_waitcnt lgkmcnt(5)
	v_add_f32_e32 v170, v170, v196
	s_waitcnt lgkmcnt(4)
	v_add_f32_e32 v171, v171, v197
	s_waitcnt lgkmcnt(3)
	v_add_f32_e32 v172, v172, v198
	s_waitcnt lgkmcnt(2)
	v_add_f32_e32 v173, v173, v199
	s_waitcnt lgkmcnt(1)
	v_add_f32_e32 v192, v192, v200
	s_waitcnt lgkmcnt(0)
	v_add_f32_e32 v193, v193, v201
	v_fmamk_f32 v168, v168, 0x3b800000, v176
	v_fmamk_f32 v169, v169, 0x3b800000, v176
	v_fmamk_f32 v170, v170, 0x3b800000, v176
	v_fmamk_f32 v171, v171, 0x3b800000, v176
	v_fmamk_f32 v172, v172, 0x3b800000, v176
	v_fmamk_f32 v173, v173, 0x3b800000, v176
	v_fmamk_f32 v192, v192, 0x3b800000, v176
	v_fmamk_f32 v193, v193, 0x3b800000, v176
	v_rsq_f32_e32 v168, v168
	v_rsq_f32_e32 v169, v169
	v_rsq_f32_e32 v170, v170
	v_rsq_f32_e32 v171, v171
	v_rsq_f32_e32 v172, v172
	v_rsq_f32_e32 v173, v173
	v_rsq_f32_e32 v192, v192
	v_rsq_f32_e32 v193, v193
	v_mul_f32_e32 v124, v124, v168
	v_mul_f32_e32 v125, v125, v168
	v_mul_f32_e32 v126, v126, v168
	v_mul_f32_e32 v127, v127, v168
	v_mul_f32_e32 v128, v128, v169
	v_mul_f32_e32 v129, v129, v169
	v_mul_f32_e32 v130, v130, v169
	v_mul_f32_e32 v131, v131, v169
	v_mul_f32_e32 v132, v132, v170
	v_mul_f32_e32 v133, v133, v170
	v_mul_f32_e32 v134, v134, v170
	v_mul_f32_e32 v135, v135, v170
	v_mul_f32_e32 v148, v148, v171
	v_mul_f32_e32 v149, v149, v171
	v_mul_f32_e32 v150, v150, v171
	v_mul_f32_e32 v151, v151, v171
	v_mul_f32_e32 v152, v152, v172
	v_mul_f32_e32 v153, v153, v172
	v_mul_f32_e32 v154, v154, v172
	v_mul_f32_e32 v155, v155, v172
	v_mul_f32_e32 v156, v156, v173
	v_mul_f32_e32 v157, v157, v173
	v_mul_f32_e32 v158, v158, v173
	v_mul_f32_e32 v159, v159, v173
	v_mul_f32_e32 v160, v160, v192
	v_mul_f32_e32 v161, v161, v192
	v_mul_f32_e32 v162, v162, v192
	v_mul_f32_e32 v163, v163, v192
	v_mul_f32_e32 v164, v164, v193
	v_mul_f32_e32 v165, v165, v193
	v_mul_f32_e32 v166, v166, v193
	v_mul_f32_e32 v167, v167, v193
	v_fma_f32 v124, v2, v124, v6
	v_fma_f32 v125, v3, v125, v7
	v_fma_f32 v126, v4, v126, v8
	v_fma_f32 v127, v5, v127, v9
	v_fma_f32 v128, v2, v128, v6
	v_fma_f32 v129, v3, v129, v7
	v_fma_f32 v130, v4, v130, v8
	v_fma_f32 v131, v5, v131, v9
	v_fma_f32 v132, v2, v132, v6
	v_fma_f32 v133, v3, v133, v7
	v_fma_f32 v134, v4, v134, v8
	v_fma_f32 v135, v5, v135, v9
	v_fma_f32 v148, v2, v148, v6
	v_fma_f32 v149, v3, v149, v7
	v_fma_f32 v150, v4, v150, v8
	v_fma_f32 v151, v5, v151, v9
	v_fma_f32 v152, v2, v152, v6
	v_fma_f32 v153, v3, v153, v7
	v_fma_f32 v154, v4, v154, v8
	v_fma_f32 v155, v5, v155, v9
	v_fma_f32 v156, v2, v156, v6
	v_fma_f32 v157, v3, v157, v7
	v_fma_f32 v158, v4, v158, v8
	v_fma_f32 v159, v5, v159, v9
	v_fma_f32 v160, v2, v160, v6
	v_fma_f32 v161, v3, v161, v7
	v_fma_f32 v162, v4, v162, v8
	v_fma_f32 v163, v5, v163, v9
	v_fma_f32 v164, v2, v164, v6
	v_fma_f32 v165, v3, v165, v7
	v_fma_f32 v166, v4, v166, v8
	v_fma_f32 v167, v5, v167, v9
	v_mul_f32_e32 v168, 0xbfb8aa3b, v124
	v_mul_f32_e32 v169, 0xbfb8aa3b, v125
	v_mul_f32_e32 v170, 0xbfb8aa3b, v126
	v_mul_f32_e32 v171, 0xbfb8aa3b, v127
	v_mul_f32_e32 v172, 0xbfb8aa3b, v128
	v_mul_f32_e32 v173, 0xbfb8aa3b, v129
	v_mul_f32_e32 v192, 0xbfb8aa3b, v130
	v_mul_f32_e32 v193, 0xbfb8aa3b, v131
	v_mul_f32_e32 v194, 0xbfb8aa3b, v132
	v_mul_f32_e32 v195, 0xbfb8aa3b, v133
	v_mul_f32_e32 v196, 0xbfb8aa3b, v134
	v_mul_f32_e32 v197, 0xbfb8aa3b, v135
	v_mul_f32_e32 v198, 0xbfb8aa3b, v148
	v_mul_f32_e32 v199, 0xbfb8aa3b, v149
	v_mul_f32_e32 v200, 0xbfb8aa3b, v150
	v_mul_f32_e32 v201, 0xbfb8aa3b, v151
	v_exp_f32_e32 v168, v168
	v_exp_f32_e32 v169, v169
	v_exp_f32_e32 v170, v170
	v_exp_f32_e32 v171, v171
	v_exp_f32_e32 v172, v172
	v_exp_f32_e32 v173, v173
	v_exp_f32_e32 v192, v192
	v_exp_f32_e32 v193, v193
	v_exp_f32_e32 v194, v194
	v_exp_f32_e32 v195, v195
	v_exp_f32_e32 v196, v196
	v_exp_f32_e32 v197, v197
	v_exp_f32_e32 v198, v198
	v_exp_f32_e32 v199, v199
	v_exp_f32_e32 v200, v200
	v_exp_f32_e32 v201, v201
	v_add_f32_e32 v168, 1.0, v168
	v_add_f32_e32 v169, 1.0, v169
	v_add_f32_e32 v170, 1.0, v170
	v_add_f32_e32 v171, 1.0, v171
	v_add_f32_e32 v172, 1.0, v172
	v_add_f32_e32 v173, 1.0, v173
	v_add_f32_e32 v192, 1.0, v192
	v_add_f32_e32 v193, 1.0, v193
	v_add_f32_e32 v194, 1.0, v194
	v_add_f32_e32 v195, 1.0, v195
	v_add_f32_e32 v196, 1.0, v196
	v_add_f32_e32 v197, 1.0, v197
	v_add_f32_e32 v198, 1.0, v198
	v_add_f32_e32 v199, 1.0, v199
; __device__ __forceinline__ unsigned cvt_pk_bf16(float lo, float hi) { unsigned r; asm volatile("v_cvt_pk_bf16_f32 %0, %1, %2" : "=v"(r) : "v"(lo), "v"(hi)); return r; }
; __device__ __forceinline__ float sigmoidf_(float x) { return __builtin_amdgcn_rcpf(1.f + __expf(-x)); }
; __device__ __forceinline__ void conv_loop(unsigned char* ws_, const float* const* in_, int l_, LAS unsigned char* lds, int tid, int bid, int G) {
;     ...
;                 const float rstd = rsqrtf(var + LN_EPS); f32x4 y = v * rstd * gg + bb;
; #pragma unroll
;                 for (int e = 0; e < 4; ++e) y[e] = y[e] * sigmoidf_(y[e]);
;                 u32x2 wv2; wv2.x = cvt_pk_bf16(y[0], y[1]); wv2.y = cvt_pk_bf16(y[2], y[3]);
;                 *(u32x2*)(X.MIX + ((size_t)b * SEQ + t0 + tok) * DM + AW + 4 * lane) = wv2; }
;             __syncthreads();
	v_add_f32_e32 v200, 1.0, v200
	v_add_f32_e32 v201, 1.0, v201
	v_rcp_f32_e32 v168, v168
	v_rcp_f32_e32 v169, v169
	v_rcp_f32_e32 v170, v170
	v_rcp_f32_e32 v171, v171
	v_rcp_f32_e32 v172, v172
	v_rcp_f32_e32 v173, v173
	v_rcp_f32_e32 v192, v192
	v_rcp_f32_e32 v193, v193
	v_rcp_f32_e32 v194, v194
	v_rcp_f32_e32 v195, v195
	v_rcp_f32_e32 v196, v196
	v_rcp_f32_e32 v197, v197
	v_rcp_f32_e32 v198, v198
	v_rcp_f32_e32 v199, v199
	v_rcp_f32_e32 v200, v200
	v_rcp_f32_e32 v201, v201
	v_mul_f32_e32 v124, v124, v168
	v_mul_f32_e32 v125, v125, v169
	v_mul_f32_e32 v126, v126, v170
	v_mul_f32_e32 v127, v127, v171
	v_mul_f32_e32 v128, v128, v172
	v_mul_f32_e32 v129, v129, v173
	v_mul_f32_e32 v130, v130, v192
	v_mul_f32_e32 v131, v131, v193
	v_mul_f32_e32 v132, v132, v194
	v_mul_f32_e32 v133, v133, v195
	v_mul_f32_e32 v134, v134, v196
	v_mul_f32_e32 v135, v135, v197
	v_mul_f32_e32 v148, v148, v198
	v_mul_f32_e32 v149, v149, v199
	v_mul_f32_e32 v150, v150, v200
	v_mul_f32_e32 v151, v151, v201
	v_cvt_pk_bf16_f32 v124, v124, v125
	v_cvt_pk_bf16_f32 v125, v126, v127
	v_cvt_pk_bf16_f32 v128, v128, v129
	v_cvt_pk_bf16_f32 v129, v130, v131
	v_cvt_pk_bf16_f32 v132, v132, v133
	v_cvt_pk_bf16_f32 v133, v134, v135
	v_cvt_pk_bf16_f32 v148, v148, v149
	v_cvt_pk_bf16_f32 v149, v150, v151
	global_store_dwordx2 v[206:207], v[124:125], off
	global_store_dwordx2 v[206:207], v[128:129], off offset:2048
	global_store_dwordx2 v[208:209], v[132:133], off
	global_store_dwordx2 v[208:209], v[148:149], off offset:2048
	v_mul_f32_e32 v168, 0xbfb8aa3b, v152
	v_mul_f32_e32 v169, 0xbfb8aa3b, v153
	v_mul_f32_e32 v170, 0xbfb8aa3b, v154
	v_mul_f32_e32 v171, 0xbfb8aa3b, v155
	v_mul_f32_e32 v172, 0xbfb8aa3b, v156
	v_mul_f32_e32 v173, 0xbfb8aa3b, v157
	v_mul_f32_e32 v192, 0xbfb8aa3b, v158
	v_mul_f32_e32 v193, 0xbfb8aa3b, v159
	v_mul_f32_e32 v194, 0xbfb8aa3b, v160
	v_mul_f32_e32 v195, 0xbfb8aa3b, v161
	v_mul_f32_e32 v196, 0xbfb8aa3b, v162
	v_mul_f32_e32 v197, 0xbfb8aa3b, v163
	v_mul_f32_e32 v198, 0xbfb8aa3b, v164
	v_mul_f32_e32 v199, 0xbfb8aa3b, v165
	v_mul_f32_e32 v200, 0xbfb8aa3b, v166
	v_mul_f32_e32 v201, 0xbfb8aa3b, v167
	v_exp_f32_e32 v168, v168
	v_exp_f32_e32 v169, v169
	v_exp_f32_e32 v170, v170
	v_exp_f32_e32 v171, v171
	v_exp_f32_e32 v172, v172
	v_exp_f32_e32 v173, v173
	v_exp_f32_e32 v192, v192
	v_exp_f32_e32 v193, v193
	v_exp_f32_e32 v194, v194
	v_exp_f32_e32 v195, v195
	v_exp_f32_e32 v196, v196
	v_exp_f32_e32 v197, v197
	v_exp_f32_e32 v198, v198
	v_exp_f32_e32 v199, v199
	v_exp_f32_e32 v200, v200
	v_exp_f32_e32 v201, v201
	v_add_f32_e32 v168, 1.0, v168
	v_add_f32_e32 v169, 1.0, v169
	v_add_f32_e32 v170, 1.0, v170
	v_add_f32_e32 v171, 1.0, v171
	v_add_f32_e32 v172, 1.0, v172
	v_add_f32_e32 v173, 1.0, v173
	v_add_f32_e32 v192, 1.0, v192
	v_add_f32_e32 v193, 1.0, v193
	v_add_f32_e32 v194, 1.0, v194
	v_add_f32_e32 v195, 1.0, v195
	v_add_f32_e32 v196, 1.0, v196
	v_add_f32_e32 v197, 1.0, v197
	v_add_f32_e32 v198, 1.0, v198
	v_add_f32_e32 v199, 1.0, v199
	v_add_f32_e32 v200, 1.0, v200
	v_add_f32_e32 v201, 1.0, v201
	v_rcp_f32_e32 v168, v168
	v_rcp_f32_e32 v169, v169
	v_rcp_f32_e32 v170, v170
	v_rcp_f32_e32 v171, v171
	v_rcp_f32_e32 v172, v172
	v_rcp_f32_e32 v173, v173
	v_rcp_f32_e32 v192, v192
	v_rcp_f32_e32 v193, v193
	v_rcp_f32_e32 v194, v194
	v_rcp_f32_e32 v195, v195
	v_rcp_f32_e32 v196, v196
	v_rcp_f32_e32 v197, v197
	v_rcp_f32_e32 v198, v198
	v_rcp_f32_e32 v199, v199
	v_rcp_f32_e32 v200, v200
	v_rcp_f32_e32 v201, v201
	v_mul_f32_e32 v152, v152, v168
	v_mul_f32_e32 v153, v153, v169
	v_mul_f32_e32 v154, v154, v170
	v_mul_f32_e32 v155, v155, v171
	v_mul_f32_e32 v156, v156, v172
	v_mul_f32_e32 v157, v157, v173
	v_mul_f32_e32 v158, v158, v192
	v_mul_f32_e32 v159, v159, v193
	v_mul_f32_e32 v160, v160, v194
	v_mul_f32_e32 v161, v161, v195
	v_mul_f32_e32 v162, v162, v196
	v_mul_f32_e32 v163, v163, v197
	v_mul_f32_e32 v164, v164, v198
	v_mul_f32_e32 v165, v165, v199
	v_mul_f32_e32 v166, v166, v200
	v_mul_f32_e32 v167, v167, v201
	v_cvt_pk_bf16_f32 v152, v152, v153
	v_cvt_pk_bf16_f32 v153, v154, v155
	v_cvt_pk_bf16_f32 v156, v156, v157
	v_cvt_pk_bf16_f32 v157, v158, v159
	v_cvt_pk_bf16_f32 v160, v160, v161
	v_cvt_pk_bf16_f32 v161, v162, v163
	v_cvt_pk_bf16_f32 v164, v164, v165
	v_cvt_pk_bf16_f32 v165, v166, v167
	global_store_dwordx2 v[210:211], v[152:153], off
	global_store_dwordx2 v[210:211], v[156:157], off offset:2048
	global_store_dwordx2 v[212:213], v[160:161], off
	global_store_dwordx2 v[212:213], v[164:165], off offset:2048
	s_cmp_eq_u32 s27, 0
	s_barrier
	s_cbranch_scc1 .LBB0_292
	ds_write_b32 v229, v214 offset:0
	ds_write_b32 v229, v215 offset:1024
	ds_write_b32 v229, v216 offset:2048
	ds_write_b32 v229, v217 offset:3072
	ds_write_b32 v229, v218 offset:4096
	ds_write_b32 v229, v219 offset:5120
	ds_write_b32 v229, v220 offset:6144
	ds_write_b32 v229, v221 offset:7168
	ds_write_b32 v229, v222 offset:8192
	ds_write_b32 v229, v223 offset:9216
	ds_write_b32 v229, v224 offset:10240
	ds_write_b32 v229, v225 offset:11264
	ds_write_b32 v229, v226 offset:12288
	ds_write_b32 v229, v227 offset:13312
	ds_write_b32 v229, v228 offset:14336
